# GEMM MFMA phases: removed the redundant mid-block s_setprio 0/1 pair and the redundant post-barrier lgkmcnt(0) (16 sites each)
# baseline (speedup 1.0000x reference)
; #define PG8_STAGE(bufoff, gbase, voff) do { _Pragma("unroll") for (int _i = 0; _i < 2; ++_i) \
;         __builtin_amdgcn_global_load_lds((const unsigned*)((const char*)(gbase) + (voff)[_i]), (PG8_LAS unsigned*)(lds + (bufoff) + ldsw + _i * 8192), 16, 0, 0); } while (0)
; #define PG8_LDA(dst, b, h) do { _Pragma("unroll") for (int m = 0; m < 4; ++m) _Pragma("unroll") for (int k = 0; k < 2; ++k) dst[m][k] = *(const PG8_LAS bf16x8*)(lds + PG8_SA(b, h) + aoff + m * 2048 + k * 1024); } while (0)
; #define PG8_LDB(dst, b, h) do { _Pragma("unroll") for (int n = 0; n < 2; ++n) _Pragma("unroll") for (int k = 0; k < 2; ++k) dst[n][k] = *(const PG8_LAS bf16x8*)(lds + PG8_SB(b, h) + boff + n * 2048 + k * 1024); } while (0)
; #define PG8_MMA(ai, bj, At, Bt) do { __builtin_amdgcn_s_setprio(1); _Pragma("unroll") for (int m = 0; m < 4; ++m) _Pragma("unroll") for (int n = 0; n < 2; ++n) _Pragma("unroll") for (int k = 0; k < 2; ++k) \
;         acc[ai][bj][m][n] = __builtin_amdgcn_mfma_f32_16x16x32_bf16(Bt[n][k], At[m][k], acc[ai][bj][m][n], 0, 0, 0); __builtin_amdgcn_s_setprio(0); } while (0)
; #define PG8_WAIT_V(n) asm volatile("s_waitcnt vmcnt(" #n ")" ::: "memory")
; #define PG8_WAIT_L(n) asm volatile("s_waitcnt lgkmcnt(" #n ")" ::: "memory")
; #define PG8_BAR __builtin_amdgcn_s_barrier()
; #define PG8_SCHED __builtin_amdgcn_sched_barrier(0)
; template <class Epi, class Sched, bool ALIGN_EPI = false, bool SP2 = false>
; __device__ __forceinline__ void gemm_phase(PG8_LAS unsigned char* lds, const Gemm g, const Sched& S, const Epi& E, int tid_in) {
;     ...
;             PG8_LDB(B0, 0, 0); PG8_LDB(B1, 0, 1); PG8_SCHED; PG8_LDA(At, 0, 0); PG8_STAGE(PG8_SA(1, 1), a1 + hstep, voffA);
;             PG8_WAIT_V(8); PG8_WAIT_L(0); PG8_BAR; PG8_MMA(0, 0, At, B0); PG8_MMA(0, 1, At, B1); PG8_BAR; PG8_SCHED;
;             PG8_LDA(At, 0, 1); PG8_STAGE(PG8_SB(0, 0), b2, voffB); PG8_STAGE(PG8_SB(0, 1), b2 + hstep, voffB); PG8_STAGE(PG8_SA(0, 0), a2, voffA);
;             PG8_WAIT_V(8); PG8_WAIT_L(0); PG8_BAR; PG8_MMA(1, 0, At, B0); PG8_MMA(1, 1, At, B1); PG8_BAR; PG8_SCHED;
.LBB0_170:
	s_add_u32 s0, s46, 0xfffc0080
	s_addc_u32 s1, s47, -1
	s_add_i32 s17, 0, 0x10000
	s_cmp_eq_u32 s67, 12
	s_cselect_b32 s19, s13, s1
	s_cselect_b32 s18, s63, s0
	v_add_u32_e32 v145, s17, v142
	s_cselect_b32 s1, s11, s66
	s_cselect_b32 s0, s64, s65
	s_add_i32 s70, 0, 0x14000
	ds_read_b128 v[160:163], v145
	ds_read_b128 v[164:167], v145 offset:1024
	ds_read_b128 v[168:171], v145 offset:2048
	ds_read_b128 v[172:175], v145 offset:3072
	v_add_u32_e32 v145, s70, v142
	ds_read_b128 v[184:187], v145
	ds_read_b128 v[188:191], v145 offset:1024
	ds_read_b128 v[192:195], v145 offset:2048
	ds_read_b128 v[196:199], v145 offset:3072
	v_lshl_add_u64 v[176:177], s[46:47], 0, v[138:139]
	s_add_i32 m0, s53, 0xc000
	ds_read_b128 v[200:203], v144
	ds_read_b128 v[204:207], v144 offset:1024
	ds_read_b128 v[208:211], v144 offset:2048
	ds_read_b128 v[212:215], v144 offset:3072
	ds_read_b128 v[216:219], v144 offset:4096
	ds_read_b128 v[220:223], v144 offset:5120
	ds_read_b128 v[224:227], v144 offset:6144
	ds_read_b128 v[228:231], v144 offset:7168
	global_load_lds_dwordx4 v[176:177], off
	v_lshl_add_u64 v[176:177], s[46:47], 0, v[140:141]
	s_add_i32 m0, s53, 0xe000
	s_nop 0
	global_load_lds_dwordx4 v[176:177], off
	s_waitcnt vmcnt(8)
	s_waitcnt lgkmcnt(0)
	s_barrier
	s_setprio 1
	v_mfma_f32_16x16x32_bf16 v[126:129], v[160:163], v[200:203], v[126:129]
	v_mfma_f32_16x16x32_bf16 v[122:125], v[168:171], v[200:203], v[122:125]
	v_mfma_f32_16x16x32_bf16 v[118:121], v[160:163], v[208:211], v[118:121]
	v_mfma_f32_16x16x32_bf16 v[114:117], v[168:171], v[208:211], v[114:117]
	v_mfma_f32_16x16x32_bf16 v[102:105], v[160:163], v[216:219], v[102:105]
	v_mfma_f32_16x16x32_bf16 v[98:101], v[168:171], v[216:219], v[98:101]
	v_mfma_f32_16x16x32_bf16 v[86:89], v[160:163], v[224:227], v[86:89]
	v_mfma_f32_16x16x32_bf16 v[82:85], v[168:171], v[224:227], v[82:85]
	v_mfma_f32_16x16x32_bf16 v[126:129], v[164:167], v[204:207], v[126:129]
	v_mfma_f32_16x16x32_bf16 v[122:125], v[172:175], v[204:207], v[122:125]
	v_mfma_f32_16x16x32_bf16 v[118:121], v[164:167], v[212:215], v[118:121]
	v_mfma_f32_16x16x32_bf16 v[114:117], v[172:175], v[212:215], v[114:117]
	v_mfma_f32_16x16x32_bf16 v[102:105], v[164:167], v[220:223], v[102:105]
	v_mfma_f32_16x16x32_bf16 v[98:101], v[172:175], v[220:223], v[98:101]
	v_mfma_f32_16x16x32_bf16 v[86:89], v[164:167], v[228:231], v[86:89]
	v_mfma_f32_16x16x32_bf16 v[82:85], v[172:175], v[228:231], v[82:85]
	v_mfma_f32_16x16x32_bf16 v[110:113], v[184:187], v[200:203], v[110:113]
	v_mfma_f32_16x16x32_bf16 v[106:109], v[192:195], v[200:203], v[106:109]
	v_mfma_f32_16x16x32_bf16 v[94:97], v[184:187], v[208:211], v[94:97]
	v_mfma_f32_16x16x32_bf16 v[90:93], v[192:195], v[208:211], v[90:93]
	v_mfma_f32_16x16x32_bf16 v[78:81], v[184:187], v[216:219], v[78:81]
	v_mfma_f32_16x16x32_bf16 v[74:77], v[192:195], v[216:219], v[74:77]
	v_mfma_f32_16x16x32_bf16 v[70:73], v[184:187], v[224:227], v[70:73]
	v_mfma_f32_16x16x32_bf16 v[66:69], v[192:195], v[224:227], v[66:69]
	v_mfma_f32_16x16x32_bf16 v[110:113], v[188:191], v[204:207], v[110:113]
	v_mfma_f32_16x16x32_bf16 v[106:109], v[196:199], v[204:207], v[106:109]
	v_mfma_f32_16x16x32_bf16 v[94:97], v[188:191], v[212:215], v[94:97]
	v_mfma_f32_16x16x32_bf16 v[90:93], v[196:199], v[212:215], v[90:93]
	v_mfma_f32_16x16x32_bf16 v[78:81], v[188:191], v[220:223], v[78:81]
	v_mfma_f32_16x16x32_bf16 v[74:77], v[196:199], v[220:223], v[74:77]
	v_mfma_f32_16x16x32_bf16 v[70:73], v[188:191], v[228:231], v[70:73]
	v_mfma_f32_16x16x32_bf16 v[66:69], v[196:199], v[228:231], v[66:69]
	s_setprio 0
	s_barrier
	s_add_i32 s17, s17, s52
	v_lshl_add_u64 v[176:177], s[0:1], 0, v[134:135]
	s_mov_b32 m0, s17
	ds_read_b128 v[200:203], v144 offset:16384
	ds_read_b128 v[204:207], v144 offset:17408
	ds_read_b128 v[208:211], v144 offset:18432
	ds_read_b128 v[212:215], v144 offset:19456
	ds_read_b128 v[216:219], v144 offset:20480
	ds_read_b128 v[220:223], v144 offset:21504
	ds_read_b128 v[224:227], v144 offset:22528
	ds_read_b128 v[228:231], v144 offset:23552
	global_load_lds_dwordx4 v[176:177], off
	s_add_i32 m0, s17, 0x2000
	s_add_u32 s68, s0, 0x40000
	v_lshl_add_u64 v[232:233], s[0:1], 0, v[130:131]
	s_addc_u32 s69, s1, 0
	s_add_i32 s17, s70, s52
	global_load_lds_dwordx4 v[232:233], off
	v_lshl_add_u64 v[234:235], s[68:69], 0, v[134:135]
	s_mov_b32 m0, s17
	v_lshl_add_u64 v[236:237], s[18:19], 0, v[132:133]
	global_load_lds_dwordx4 v[234:235], off
	v_lshl_add_u64 v[234:235], s[68:69], 0, v[130:131]
	s_add_i32 m0, s17, 0x2000
	s_nop 0
	global_load_lds_dwordx4 v[234:235], off
	v_lshl_add_u64 v[234:235], s[18:19], 0, v[136:137]
	s_mov_b32 m0, s53
	s_nop 0
	global_load_lds_dwordx4 v[234:235], off
	s_mov_b32 m0, s54
	s_nop 0
	global_load_lds_dwordx4 v[236:237], off
	s_waitcnt vmcnt(8)
	s_waitcnt lgkmcnt(0)
	s_barrier
; #define PG8_STAGE(bufoff, gbase, voff) do { _Pragma("unroll") for (int _i = 0; _i < 2; ++_i) \
;         __builtin_amdgcn_global_load_lds((const unsigned*)((const char*)(gbase) + (voff)[_i]), (PG8_LAS unsigned*)(lds + (bufoff) + ldsw + _i * 8192), 16, 0, 0); } while (0)
; #define PG8_LDA(dst, b, h) do { _Pragma("unroll") for (int m = 0; m < 4; ++m) _Pragma("unroll") for (int k = 0; k < 2; ++k) dst[m][k] = *(const PG8_LAS bf16x8*)(lds + PG8_SA(b, h) + aoff + m * 2048 + k * 1024); } while (0)
; #define PG8_LDB(dst, b, h) do { _Pragma("unroll") for (int n = 0; n < 2; ++n) _Pragma("unroll") for (int k = 0; k < 2; ++k) dst[n][k] = *(const PG8_LAS bf16x8*)(lds + PG8_SB(b, h) + boff + n * 2048 + k * 1024); } while (0)
; #define PG8_MMA(ai, bj, At, Bt) do { __builtin_amdgcn_s_setprio(1); _Pragma("unroll") for (int m = 0; m < 4; ++m) _Pragma("unroll") for (int n = 0; n < 2; ++n) _Pragma("unroll") for (int k = 0; k < 2; ++k) \
;         acc[ai][bj][m][n] = __builtin_amdgcn_mfma_f32_16x16x32_bf16(Bt[n][k], At[m][k], acc[ai][bj][m][n], 0, 0, 0); __builtin_amdgcn_s_setprio(0); } while (0)
; #define PG8_WAIT_V(n) asm volatile("s_waitcnt vmcnt(" #n ")" ::: "memory")
; #define PG8_WAIT_L(n) asm volatile("s_waitcnt lgkmcnt(" #n ")" ::: "memory")
; #define PG8_BAR __builtin_amdgcn_s_barrier()
; #define PG8_SCHED __builtin_amdgcn_sched_barrier(0)
; template <class Epi, class Sched, bool ALIGN_EPI = false, bool SP2 = false>
; __device__ __forceinline__ void gemm_phase(PG8_LAS unsigned char* lds, const Gemm g, const Sched& S, const Epi& E, int tid_in) {
;     ...
;             PG8_WAIT_V(8); PG8_WAIT_L(0); PG8_BAR; PG8_MMA(1, 0, At, B0); PG8_MMA(1, 1, At, B1); PG8_BAR; PG8_SCHED;
;             PG8_LDB(B0, 1, 0); PG8_LDB(B1, 1, 1); PG8_SCHED; PG8_LDA(At, 1, 0); PG8_STAGE(PG8_SA(0, 1), a2 + hstep, voffA);
;             PG8_WAIT_V(8); PG8_WAIT_L(0); PG8_BAR; PG8_MMA(0, 0, At, B0); PG8_MMA(0, 1, At, B1); PG8_BAR; PG8_SCHED;
	s_setprio 1
	v_mfma_f32_16x16x32_bf16 v[62:65], v[160:163], v[200:203], v[62:65]
	v_mfma_f32_16x16x32_bf16 v[58:61], v[168:171], v[200:203], v[58:61]
	v_mfma_f32_16x16x32_bf16 v[54:57], v[160:163], v[208:211], v[54:57]
	v_mfma_f32_16x16x32_bf16 v[50:53], v[168:171], v[208:211], v[50:53]
	v_mfma_f32_16x16x32_bf16 v[38:41], v[160:163], v[216:219], v[38:41]
	v_mfma_f32_16x16x32_bf16 v[34:37], v[168:171], v[216:219], v[34:37]
	v_mfma_f32_16x16x32_bf16 v[22:25], v[160:163], v[224:227], v[22:25]
	v_mfma_f32_16x16x32_bf16 v[18:21], v[168:171], v[224:227], v[18:21]
	v_mfma_f32_16x16x32_bf16 v[62:65], v[164:167], v[204:207], v[62:65]
	v_mfma_f32_16x16x32_bf16 v[58:61], v[172:175], v[204:207], v[58:61]
	v_mfma_f32_16x16x32_bf16 v[54:57], v[164:167], v[212:215], v[54:57]
	v_mfma_f32_16x16x32_bf16 v[50:53], v[172:175], v[212:215], v[50:53]
	v_mfma_f32_16x16x32_bf16 v[38:41], v[164:167], v[220:223], v[38:41]
	v_mfma_f32_16x16x32_bf16 v[34:37], v[172:175], v[220:223], v[34:37]
	v_mfma_f32_16x16x32_bf16 v[22:25], v[164:167], v[228:231], v[22:25]
	v_mfma_f32_16x16x32_bf16 v[18:21], v[172:175], v[228:231], v[18:21]
	v_mfma_f32_16x16x32_bf16 v[46:49], v[184:187], v[200:203], v[46:49]
	v_mfma_f32_16x16x32_bf16 v[42:45], v[192:195], v[200:203], v[42:45]
	v_mfma_f32_16x16x32_bf16 v[30:33], v[184:187], v[208:211], v[30:33]
	v_mfma_f32_16x16x32_bf16 v[26:29], v[192:195], v[208:211], v[26:29]
	v_mfma_f32_16x16x32_bf16 v[14:17], v[184:187], v[216:219], v[14:17]
	v_mfma_f32_16x16x32_bf16 v[10:13], v[192:195], v[216:219], v[10:13]
	v_mfma_f32_16x16x32_bf16 v[6:9], v[184:187], v[224:227], v[6:9]
	v_mfma_f32_16x16x32_bf16 v[2:5], v[192:195], v[224:227], v[2:5]
	v_mfma_f32_16x16x32_bf16 v[46:49], v[188:191], v[204:207], v[46:49]
	v_mfma_f32_16x16x32_bf16 v[42:45], v[196:199], v[204:207], v[42:45]
	v_mfma_f32_16x16x32_bf16 v[30:33], v[188:191], v[212:215], v[30:33]
	v_mfma_f32_16x16x32_bf16 v[26:29], v[196:199], v[212:215], v[26:29]
	v_mfma_f32_16x16x32_bf16 v[14:17], v[188:191], v[220:223], v[14:17]
	v_mfma_f32_16x16x32_bf16 v[10:13], v[196:199], v[220:223], v[10:13]
	v_mfma_f32_16x16x32_bf16 v[6:9], v[188:191], v[228:231], v[6:9]
	v_mfma_f32_16x16x32_bf16 v[2:5], v[196:199], v[228:231], v[2:5]
	s_setprio 0
	s_barrier
	s_add_i32 s17, 0, 0x18000
	v_add_u32_e32 v145, s17, v142
	s_add_i32 s68, 0, 0x1c000
	ds_read_b128 v[160:163], v145
	ds_read_b128 v[164:167], v145 offset:1024
	ds_read_b128 v[168:171], v145 offset:2048
	ds_read_b128 v[172:175], v145 offset:3072
	v_add_u32_e32 v145, s68, v142
	ds_read_b128 v[184:187], v145
	ds_read_b128 v[188:191], v145 offset:1024
	ds_read_b128 v[192:195], v145 offset:2048
	ds_read_b128 v[196:199], v145 offset:3072
	s_add_u32 s18, s18, 0x40000
	s_addc_u32 s19, s19, 0
	s_mov_b32 m0, s55
	v_lshl_add_u64 v[238:239], s[18:19], 0, v[136:137]
	ds_read_b128 v[200:203], v144 offset:32768
	ds_read_b128 v[204:207], v144 offset:33792
	ds_read_b128 v[208:211], v144 offset:34816
	ds_read_b128 v[212:215], v144 offset:35840
	ds_read_b128 v[216:219], v144 offset:36864
	ds_read_b128 v[220:223], v144 offset:37888
	ds_read_b128 v[224:227], v144 offset:38912
	ds_read_b128 v[228:231], v144 offset:39936
	global_load_lds_dwordx4 v[238:239], off
	v_lshl_add_u64 v[238:239], s[18:19], 0, v[132:133]
	s_mov_b32 m0, s58
	s_nop 0
	global_load_lds_dwordx4 v[238:239], off
	s_waitcnt vmcnt(8)
	s_waitcnt lgkmcnt(0)
	s_barrier
	s_setprio 1
	v_mfma_f32_16x16x32_bf16 v[126:129], v[160:163], v[200:203], v[126:129]
	v_mfma_f32_16x16x32_bf16 v[122:125], v[168:171], v[200:203], v[122:125]
	v_mfma_f32_16x16x32_bf16 v[118:121], v[160:163], v[208:211], v[118:121]
	v_mfma_f32_16x16x32_bf16 v[114:117], v[168:171], v[208:211], v[114:117]
	v_mfma_f32_16x16x32_bf16 v[102:105], v[160:163], v[216:219], v[102:105]
	v_mfma_f32_16x16x32_bf16 v[98:101], v[168:171], v[216:219], v[98:101]
	v_mfma_f32_16x16x32_bf16 v[86:89], v[160:163], v[224:227], v[86:89]
	v_mfma_f32_16x16x32_bf16 v[82:85], v[168:171], v[224:227], v[82:85]
	v_mfma_f32_16x16x32_bf16 v[126:129], v[164:167], v[204:207], v[126:129]
	v_mfma_f32_16x16x32_bf16 v[122:125], v[172:175], v[204:207], v[122:125]
	v_mfma_f32_16x16x32_bf16 v[118:121], v[164:167], v[212:215], v[118:121]
	v_mfma_f32_16x16x32_bf16 v[114:117], v[172:175], v[212:215], v[114:117]
	v_mfma_f32_16x16x32_bf16 v[102:105], v[164:167], v[220:223], v[102:105]
	v_mfma_f32_16x16x32_bf16 v[98:101], v[172:175], v[220:223], v[98:101]
	v_mfma_f32_16x16x32_bf16 v[86:89], v[164:167], v[228:231], v[86:89]
	v_mfma_f32_16x16x32_bf16 v[82:85], v[172:175], v[228:231], v[82:85]
	v_mfma_f32_16x16x32_bf16 v[110:113], v[184:187], v[200:203], v[110:113]
	v_mfma_f32_16x16x32_bf16 v[106:109], v[192:195], v[200:203], v[106:109]
	v_mfma_f32_16x16x32_bf16 v[94:97], v[184:187], v[208:211], v[94:97]
	v_mfma_f32_16x16x32_bf16 v[90:93], v[192:195], v[208:211], v[90:93]
	v_mfma_f32_16x16x32_bf16 v[78:81], v[184:187], v[216:219], v[78:81]
	v_mfma_f32_16x16x32_bf16 v[74:77], v[192:195], v[216:219], v[74:77]
	v_mfma_f32_16x16x32_bf16 v[70:73], v[184:187], v[224:227], v[70:73]
	v_mfma_f32_16x16x32_bf16 v[66:69], v[192:195], v[224:227], v[66:69]
	v_mfma_f32_16x16x32_bf16 v[110:113], v[188:191], v[204:207], v[110:113]
	v_mfma_f32_16x16x32_bf16 v[106:109], v[196:199], v[204:207], v[106:109]
	v_mfma_f32_16x16x32_bf16 v[94:97], v[188:191], v[212:215], v[94:97]
	v_mfma_f32_16x16x32_bf16 v[90:93], v[196:199], v[212:215], v[90:93]
	v_mfma_f32_16x16x32_bf16 v[78:81], v[188:191], v[220:223], v[78:81]
	v_mfma_f32_16x16x32_bf16 v[74:77], v[196:199], v[220:223], v[74:77]
	v_mfma_f32_16x16x32_bf16 v[70:73], v[188:191], v[228:231], v[70:73]
	v_mfma_f32_16x16x32_bf16 v[66:69], v[196:199], v[228:231], v[66:69]
	s_setprio 0
	s_barrier
; #define PG8_STAGE(bufoff, gbase, voff) do { _Pragma("unroll") for (int _i = 0; _i < 2; ++_i) \
;         __builtin_amdgcn_global_load_lds((const unsigned*)((const char*)(gbase) + (voff)[_i]), (PG8_LAS unsigned*)(lds + (bufoff) + ldsw + _i * 8192), 16, 0, 0); } while (0)
; #define PG8_LDA(dst, b, h) do { _Pragma("unroll") for (int m = 0; m < 4; ++m) _Pragma("unroll") for (int k = 0; k < 2; ++k) dst[m][k] = *(const PG8_LAS bf16x8*)(lds + PG8_SA(b, h) + aoff + m * 2048 + k * 1024); } while (0)
; #define PG8_MMA(ai, bj, At, Bt) do { __builtin_amdgcn_s_setprio(1); _Pragma("unroll") for (int m = 0; m < 4; ++m) _Pragma("unroll") for (int n = 0; n < 2; ++n) _Pragma("unroll") for (int k = 0; k < 2; ++k) \
;         acc[ai][bj][m][n] = __builtin_amdgcn_mfma_f32_16x16x32_bf16(Bt[n][k], At[m][k], acc[ai][bj][m][n], 0, 0, 0); __builtin_amdgcn_s_setprio(0); } while (0)
; #define PG8_WAIT_V(n) asm volatile("s_waitcnt vmcnt(" #n ")" ::: "memory")
; #define PG8_WAIT_L(n) asm volatile("s_waitcnt lgkmcnt(" #n ")" ::: "memory")
; #define PG8_BAR __builtin_amdgcn_s_barrier()
; #define PG8_SCHED __builtin_amdgcn_sched_barrier(0)
; template <class Epi, class Sched, bool ALIGN_EPI = false, bool SP2 = false>
; __device__ __forceinline__ void gemm_phase(PG8_LAS unsigned char* lds, const Gemm g, const Sched& S, const Epi& E, int tid_in) {
;     ...
;         for (int t = 0; t < nt; t += 2) {
;     ...
;             PG8_LDA(At, 1, 1); PG8_STAGE(PG8_SB(1, 0), b3, voffB); PG8_STAGE(PG8_SB(1, 1), b3 + hstep, voffB); PG8_STAGE(PG8_SA(1, 0), a3, voffA);
;             PG8_WAIT_V(8); PG8_WAIT_L(0); PG8_BAR; PG8_MMA(1, 0, At, B0); PG8_MMA(1, 1, At, B1); PG8_BAR; PG8_SCHED;
	s_add_i32 s17, s17, s52
	v_lshl_add_u64 v[176:177], v[176:177], 0, s[94:95]
	s_mov_b32 m0, s17
	ds_read_b128 v[200:203], v144 offset:49152
	ds_read_b128 v[204:207], v144 offset:50176
	ds_read_b128 v[208:211], v144 offset:51200
	ds_read_b128 v[212:215], v144 offset:52224
	ds_read_b128 v[216:219], v144 offset:53248
	ds_read_b128 v[220:223], v144 offset:54272
	ds_read_b128 v[224:227], v144 offset:55296
	ds_read_b128 v[228:231], v144 offset:56320
	global_load_lds_dwordx4 v[176:177], off
	s_add_i32 m0, s17, 0x2000
	s_add_u32 s0, s0, 0x40080
	v_lshl_add_u64 v[176:177], v[232:233], 0, s[94:95]
	s_addc_u32 s1, s1, 0
	s_add_i32 s17, s68, s52
	global_load_lds_dwordx4 v[176:177], off
	v_lshl_add_u64 v[176:177], s[0:1], 0, v[134:135]
	s_mov_b32 m0, s17
	s_nop 0
	global_load_lds_dwordx4 v[176:177], off
	v_lshl_add_u64 v[176:177], s[0:1], 0, v[130:131]
	s_add_i32 m0, s17, 0x2000
	s_nop 0
	global_load_lds_dwordx4 v[176:177], off
	v_lshl_add_u64 v[176:177], v[234:235], 0, s[94:95]
	s_mov_b32 m0, s59
	s_nop 0
	global_load_lds_dwordx4 v[176:177], off
	v_lshl_add_u64 v[176:177], v[236:237], 0, s[94:95]
	s_mov_b32 m0, s60
	s_nop 0
	global_load_lds_dwordx4 v[176:177], off
	s_waitcnt vmcnt(8)
	s_waitcnt lgkmcnt(0)
	s_barrier
	s_setprio 1
	v_mfma_f32_16x16x32_bf16 v[62:65], v[160:163], v[200:203], v[62:65]
	v_mfma_f32_16x16x32_bf16 v[58:61], v[168:171], v[200:203], v[58:61]
	v_mfma_f32_16x16x32_bf16 v[54:57], v[160:163], v[208:211], v[54:57]
	v_mfma_f32_16x16x32_bf16 v[50:53], v[168:171], v[208:211], v[50:53]
	v_mfma_f32_16x16x32_bf16 v[38:41], v[160:163], v[216:219], v[38:41]
	v_mfma_f32_16x16x32_bf16 v[34:37], v[168:171], v[216:219], v[34:37]
	v_mfma_f32_16x16x32_bf16 v[22:25], v[160:163], v[224:227], v[22:25]
	v_mfma_f32_16x16x32_bf16 v[18:21], v[168:171], v[224:227], v[18:21]
	v_mfma_f32_16x16x32_bf16 v[62:65], v[164:167], v[204:207], v[62:65]
	v_mfma_f32_16x16x32_bf16 v[58:61], v[172:175], v[204:207], v[58:61]
	v_mfma_f32_16x16x32_bf16 v[54:57], v[164:167], v[212:215], v[54:57]
	v_mfma_f32_16x16x32_bf16 v[50:53], v[172:175], v[212:215], v[50:53]
	v_mfma_f32_16x16x32_bf16 v[38:41], v[164:167], v[220:223], v[38:41]
	v_mfma_f32_16x16x32_bf16 v[34:37], v[172:175], v[220:223], v[34:37]
	v_mfma_f32_16x16x32_bf16 v[22:25], v[164:167], v[228:231], v[22:25]
	v_mfma_f32_16x16x32_bf16 v[18:21], v[172:175], v[228:231], v[18:21]
	v_mfma_f32_16x16x32_bf16 v[46:49], v[184:187], v[200:203], v[46:49]
	v_mfma_f32_16x16x32_bf16 v[42:45], v[192:195], v[200:203], v[42:45]
	v_mfma_f32_16x16x32_bf16 v[30:33], v[184:187], v[208:211], v[30:33]
	v_mfma_f32_16x16x32_bf16 v[26:29], v[192:195], v[208:211], v[26:29]
	v_mfma_f32_16x16x32_bf16 v[14:17], v[184:187], v[216:219], v[14:17]
	v_mfma_f32_16x16x32_bf16 v[10:13], v[192:195], v[216:219], v[10:13]
	v_mfma_f32_16x16x32_bf16 v[6:9], v[184:187], v[224:227], v[6:9]
	v_mfma_f32_16x16x32_bf16 v[2:5], v[192:195], v[224:227], v[2:5]
	v_mfma_f32_16x16x32_bf16 v[46:49], v[188:191], v[204:207], v[46:49]
	v_mfma_f32_16x16x32_bf16 v[42:45], v[196:199], v[204:207], v[42:45]
	v_mfma_f32_16x16x32_bf16 v[30:33], v[188:191], v[212:215], v[30:33]
	v_mfma_f32_16x16x32_bf16 v[26:29], v[196:199], v[212:215], v[26:29]
	v_mfma_f32_16x16x32_bf16 v[14:17], v[188:191], v[220:223], v[14:17]
	v_mfma_f32_16x16x32_bf16 v[10:13], v[196:199], v[220:223], v[10:13]
	v_mfma_f32_16x16x32_bf16 v[6:9], v[188:191], v[228:231], v[6:9]
	v_mfma_f32_16x16x32_bf16 v[2:5], v[196:199], v[228:231], v[2:5]
	s_setprio 0
	s_barrier
	s_add_i32 s67, s67, 2
	s_add_u32 s46, s46, 0x100
	s_addc_u32 s47, s47, 0
	s_add_u32 s65, s65, 0x100
	s_addc_u32 s66, s66, 0
	s_cmp_gt_u32 s67, 13
	s_cbranch_scc0 .LBB0_170
	s_and_b64 vcc, exec, s[8:9]
	s_cbranch_vccz .LBB0_173
	s_barrier

; #define PG8_STAGE(bufoff, gbase, voff) do { _Pragma("unroll") for (int _i = 0; _i < 2; ++_i) \
;         __builtin_amdgcn_global_load_lds((const unsigned*)((const char*)(gbase) + (voff)[_i]), (PG8_LAS unsigned*)(lds + (bufoff) + ldsw + _i * 8192), 16, 0, 0); } while (0)
; #define PG8_LDA(dst, b, h) do { _Pragma("unroll") for (int m = 0; m < 4; ++m) _Pragma("unroll") for (int k = 0; k < 2; ++k) dst[m][k] = *(const PG8_LAS bf16x8*)(lds + PG8_SA(b, h) + aoff + m * 2048 + k * 1024); } while (0)
; #define PG8_LDB(dst, b, h) do { _Pragma("unroll") for (int n = 0; n < 2; ++n) _Pragma("unroll") for (int k = 0; k < 2; ++k) dst[n][k] = *(const PG8_LAS bf16x8*)(lds + PG8_SB(b, h) + boff + n * 2048 + k * 1024); } while (0)
; #define PG8_MMA(ai, bj, At, Bt) do { __builtin_amdgcn_s_setprio(1); _Pragma("unroll") for (int m = 0; m < 4; ++m) _Pragma("unroll") for (int n = 0; n < 2; ++n) _Pragma("unroll") for (int k = 0; k < 2; ++k) \
;         acc[ai][bj][m][n] = __builtin_amdgcn_mfma_f32_16x16x32_bf16(Bt[n][k], At[m][k], acc[ai][bj][m][n], 0, 0, 0); __builtin_amdgcn_s_setprio(0); } while (0)
; #define PG8_WAIT_V(n) asm volatile("s_waitcnt vmcnt(" #n ")" ::: "memory")
; #define PG8_WAIT_L(n) asm volatile("s_waitcnt lgkmcnt(" #n ")" ::: "memory")
; #define PG8_BAR __builtin_amdgcn_s_barrier()
; #define PG8_SCHED __builtin_amdgcn_sched_barrier(0)
; template <class Epi, class Sched, bool ALIGN_EPI = false, bool SP2 = false>
; __device__ __forceinline__ void gemm_phase(PG8_LAS unsigned char* lds, const Gemm g, const Sched& S, const Epi& E, int tid_in) {
;     ...
;             PG8_LDB(B0, 0, 0); PG8_LDB(B1, 0, 1); PG8_SCHED; PG8_LDA(At, 0, 0); PG8_STAGE(PG8_SA(1, 1), a1 + hstep, voffA);
;             PG8_WAIT_V(8); PG8_WAIT_L(0); PG8_BAR; PG8_MMA(0, 0, At, B0); PG8_MMA(0, 1, At, B1); PG8_BAR; PG8_SCHED;
;             PG8_LDA(At, 0, 1); PG8_STAGE(PG8_SB(0, 0), b2, voffB); PG8_STAGE(PG8_SB(0, 1), b2 + hstep, voffB); PG8_STAGE(PG8_SA(0, 0), a2, voffA);
;             PG8_WAIT_V(8); PG8_WAIT_L(0); PG8_BAR; PG8_MMA(1, 0, At, B0); PG8_MMA(1, 1, At, B1); PG8_BAR; PG8_SCHED;
.LBB0_855:
	s_add_u32 s54, s52, 0x100
	s_addc_u32 s55, s53, 0
	s_add_i32 s17, 0, 0x10000
	s_cmp_eq_u32 s94, 12
	s_cselect_b32 s19, s41, s55
	s_cselect_b32 s18, s84, s54
	s_cselect_b32 s1, s13, s89
	s_cselect_b32 s0, s85, s88
	s_add_i32 s79, 0, 0x14000
	v_add_u32_e32 v130, s17, v176
	v_add_u32_e32 v188, s79, v176
	ds_read_b128 v[114:117], v130
	ds_read_b128 v[118:121], v130 offset:1024
	ds_read_b128 v[126:129], v130 offset:2048
	ds_read_b128 v[130:133], v130 offset:3072
	ds_read_b128 v[168:171], v188
	ds_read_b128 v[172:175], v188 offset:1024
	ds_read_b128 v[184:187], v188 offset:2048
	ds_read_b128 v[188:191], v188 offset:3072
	v_lshl_add_u64 v[224:225], s[52:53], 0, v[164:165]
	s_add_i32 m0, s63, 0xc000
	ds_read_b128 v[192:195], v183
	ds_read_b128 v[196:199], v183 offset:1024
	ds_read_b128 v[200:203], v183 offset:2048
	ds_read_b128 v[204:207], v183 offset:3072
	ds_read_b128 v[208:211], v183 offset:4096
	ds_read_b128 v[212:215], v183 offset:5120
	ds_read_b128 v[216:219], v183 offset:6144
	ds_read_b128 v[220:223], v183 offset:7168
	global_load_lds_dwordx4 v[224:225], off
	v_lshl_add_u64 v[224:225], s[52:53], 0, v[166:167]
	s_add_i32 m0, s63, 0xe000
	s_nop 0
	global_load_lds_dwordx4 v[224:225], off
	s_waitcnt vmcnt(8)
	s_waitcnt lgkmcnt(0)
	s_barrier
	s_setprio 1
	v_mfma_f32_16x16x32_bf16 v[142:145], v[114:117], v[192:195], v[142:145]
	v_mfma_f32_16x16x32_bf16 v[138:141], v[126:129], v[192:195], v[138:141]
	v_mfma_f32_16x16x32_bf16 v[110:113], v[114:117], v[200:203], v[110:113]
	v_mfma_f32_16x16x32_bf16 v[106:109], v[126:129], v[200:203], v[106:109]
	v_mfma_f32_16x16x32_bf16 v[94:97], v[114:117], v[208:211], v[94:97]
	v_mfma_f32_16x16x32_bf16 v[90:93], v[126:129], v[208:211], v[90:93]
	v_mfma_f32_16x16x32_bf16 v[78:81], v[114:117], v[216:219], v[78:81]
	v_mfma_f32_16x16x32_bf16 v[74:77], v[126:129], v[216:219], v[74:77]
	v_mfma_f32_16x16x32_bf16 v[142:145], v[118:121], v[196:199], v[142:145]
	v_mfma_f32_16x16x32_bf16 v[138:141], v[130:133], v[196:199], v[138:141]
	v_mfma_f32_16x16x32_bf16 v[110:113], v[118:121], v[204:207], v[110:113]
	v_mfma_f32_16x16x32_bf16 v[106:109], v[130:133], v[204:207], v[106:109]
	v_mfma_f32_16x16x32_bf16 v[94:97], v[118:121], v[212:215], v[94:97]
	v_mfma_f32_16x16x32_bf16 v[90:93], v[130:133], v[212:215], v[90:93]
	v_mfma_f32_16x16x32_bf16 v[78:81], v[118:121], v[220:223], v[78:81]
	v_mfma_f32_16x16x32_bf16 v[74:77], v[130:133], v[220:223], v[74:77]
	v_mfma_f32_16x16x32_bf16 v[134:137], v[168:171], v[192:195], v[134:137]
	v_mfma_f32_16x16x32_bf16 v[122:125], v[184:187], v[192:195], v[122:125]
	v_mfma_f32_16x16x32_bf16 v[102:105], v[168:171], v[200:203], v[102:105]
	v_mfma_f32_16x16x32_bf16 v[98:101], v[184:187], v[200:203], v[98:101]
	v_mfma_f32_16x16x32_bf16 v[86:89], v[168:171], v[208:211], v[86:89]
	v_mfma_f32_16x16x32_bf16 v[82:85], v[184:187], v[208:211], v[82:85]
	v_mfma_f32_16x16x32_bf16 v[70:73], v[168:171], v[216:219], v[70:73]
	v_mfma_f32_16x16x32_bf16 v[66:69], v[184:187], v[216:219], v[66:69]
	v_mfma_f32_16x16x32_bf16 v[134:137], v[172:175], v[196:199], v[134:137]
	v_mfma_f32_16x16x32_bf16 v[122:125], v[188:191], v[196:199], v[122:125]
	v_mfma_f32_16x16x32_bf16 v[102:105], v[172:175], v[204:207], v[102:105]
	v_mfma_f32_16x16x32_bf16 v[98:101], v[188:191], v[204:207], v[98:101]
	v_mfma_f32_16x16x32_bf16 v[86:89], v[172:175], v[212:215], v[86:89]
	v_mfma_f32_16x16x32_bf16 v[82:85], v[188:191], v[212:215], v[82:85]
	v_mfma_f32_16x16x32_bf16 v[70:73], v[172:175], v[220:223], v[70:73]
	v_mfma_f32_16x16x32_bf16 v[66:69], v[188:191], v[220:223], v[66:69]
	s_setprio 0
	s_barrier
	s_add_i32 s17, s17, s62
	v_lshl_add_u64 v[224:225], s[0:1], 0, v[162:163]
	s_mov_b32 m0, s17
	ds_read_b128 v[192:195], v183 offset:16384
	ds_read_b128 v[196:199], v183 offset:17408
	ds_read_b128 v[200:203], v183 offset:18432
	ds_read_b128 v[204:207], v183 offset:19456
	ds_read_b128 v[208:211], v183 offset:20480
	ds_read_b128 v[212:215], v183 offset:21504
	ds_read_b128 v[216:219], v183 offset:22528
	ds_read_b128 v[220:223], v183 offset:23552
	global_load_lds_dwordx4 v[224:225], off
	s_add_i32 m0, s17, 0x2000
	s_add_u32 s52, s0, 0x40000
	v_lshl_add_u64 v[226:227], s[0:1], 0, v[160:161]
	s_addc_u32 s53, s1, 0
	s_add_i32 s17, s79, s62
	global_load_lds_dwordx4 v[226:227], off
	v_lshl_add_u64 v[228:229], s[52:53], 0, v[162:163]
	s_mov_b32 m0, s17
	v_lshl_add_u64 v[230:231], s[18:19], 0, v[160:161]
	global_load_lds_dwordx4 v[228:229], off
	v_lshl_add_u64 v[228:229], s[52:53], 0, v[160:161]
	s_add_i32 m0, s17, 0x2000
	s_nop 0
	global_load_lds_dwordx4 v[228:229], off
	v_lshl_add_u64 v[228:229], s[18:19], 0, v[162:163]
	s_mov_b32 m0, s63
	s_nop 0
	global_load_lds_dwordx4 v[228:229], off
	s_mov_b32 m0, s64
	s_nop 0
	global_load_lds_dwordx4 v[230:231], off
	s_waitcnt vmcnt(8)
	s_waitcnt lgkmcnt(0)
	s_barrier
; #define PG8_STAGE(bufoff, gbase, voff) do { _Pragma("unroll") for (int _i = 0; _i < 2; ++_i) \
;         __builtin_amdgcn_global_load_lds((const unsigned*)((const char*)(gbase) + (voff)[_i]), (PG8_LAS unsigned*)(lds + (bufoff) + ldsw + _i * 8192), 16, 0, 0); } while (0)
; #define PG8_LDA(dst, b, h) do { _Pragma("unroll") for (int m = 0; m < 4; ++m) _Pragma("unroll") for (int k = 0; k < 2; ++k) dst[m][k] = *(const PG8_LAS bf16x8*)(lds + PG8_SA(b, h) + aoff + m * 2048 + k * 1024); } while (0)
; #define PG8_LDB(dst, b, h) do { _Pragma("unroll") for (int n = 0; n < 2; ++n) _Pragma("unroll") for (int k = 0; k < 2; ++k) dst[n][k] = *(const PG8_LAS bf16x8*)(lds + PG8_SB(b, h) + boff + n * 2048 + k * 1024); } while (0)
; #define PG8_MMA(ai, bj, At, Bt) do { __builtin_amdgcn_s_setprio(1); _Pragma("unroll") for (int m = 0; m < 4; ++m) _Pragma("unroll") for (int n = 0; n < 2; ++n) _Pragma("unroll") for (int k = 0; k < 2; ++k) \
;         acc[ai][bj][m][n] = __builtin_amdgcn_mfma_f32_16x16x32_bf16(Bt[n][k], At[m][k], acc[ai][bj][m][n], 0, 0, 0); __builtin_amdgcn_s_setprio(0); } while (0)
; #define PG8_WAIT_V(n) asm volatile("s_waitcnt vmcnt(" #n ")" ::: "memory")
; #define PG8_WAIT_L(n) asm volatile("s_waitcnt lgkmcnt(" #n ")" ::: "memory")
; #define PG8_BAR __builtin_amdgcn_s_barrier()
; #define PG8_SCHED __builtin_amdgcn_sched_barrier(0)
; template <class Epi, class Sched, bool ALIGN_EPI = false, bool SP2 = false>
; __device__ __forceinline__ void gemm_phase(PG8_LAS unsigned char* lds, const Gemm g, const Sched& S, const Epi& E, int tid_in) {
;     ...
;             PG8_WAIT_V(8); PG8_WAIT_L(0); PG8_BAR; PG8_MMA(1, 0, At, B0); PG8_MMA(1, 1, At, B1); PG8_BAR; PG8_SCHED;
;             PG8_LDB(B0, 1, 0); PG8_LDB(B1, 1, 1); PG8_SCHED; PG8_LDA(At, 1, 0); PG8_STAGE(PG8_SA(0, 1), a2 + hstep, voffA);
;             PG8_WAIT_V(8); PG8_WAIT_L(0); PG8_BAR; PG8_MMA(0, 0, At, B0); PG8_MMA(0, 1, At, B1); PG8_BAR; PG8_SCHED;
	s_setprio 1
	v_mfma_f32_16x16x32_bf16 v[62:65], v[114:117], v[192:195], v[62:65]
	v_mfma_f32_16x16x32_bf16 v[58:61], v[126:129], v[192:195], v[58:61]
	v_mfma_f32_16x16x32_bf16 v[46:49], v[114:117], v[200:203], v[46:49]
	v_mfma_f32_16x16x32_bf16 v[42:45], v[126:129], v[200:203], v[42:45]
	v_mfma_f32_16x16x32_bf16 v[30:33], v[114:117], v[208:211], v[30:33]
	v_mfma_f32_16x16x32_bf16 v[26:29], v[126:129], v[208:211], v[26:29]
	v_mfma_f32_16x16x32_bf16 v[14:17], v[114:117], v[216:219], v[14:17]
	v_mfma_f32_16x16x32_bf16 v[10:13], v[126:129], v[216:219], v[10:13]
	v_mfma_f32_16x16x32_bf16 v[62:65], v[118:121], v[196:199], v[62:65]
	v_mfma_f32_16x16x32_bf16 v[58:61], v[130:133], v[196:199], v[58:61]
	v_mfma_f32_16x16x32_bf16 v[46:49], v[118:121], v[204:207], v[46:49]
	v_mfma_f32_16x16x32_bf16 v[42:45], v[130:133], v[204:207], v[42:45]
	v_mfma_f32_16x16x32_bf16 v[30:33], v[118:121], v[212:215], v[30:33]
	v_mfma_f32_16x16x32_bf16 v[26:29], v[130:133], v[212:215], v[26:29]
	v_mfma_f32_16x16x32_bf16 v[14:17], v[118:121], v[220:223], v[14:17]
	v_mfma_f32_16x16x32_bf16 v[10:13], v[130:133], v[220:223], v[10:13]
	v_mfma_f32_16x16x32_bf16 v[54:57], v[168:171], v[192:195], v[54:57]
	v_mfma_f32_16x16x32_bf16 v[50:53], v[184:187], v[192:195], v[50:53]
	v_mfma_f32_16x16x32_bf16 v[38:41], v[168:171], v[200:203], v[38:41]
	v_mfma_f32_16x16x32_bf16 v[34:37], v[184:187], v[200:203], v[34:37]
	v_mfma_f32_16x16x32_bf16 v[22:25], v[168:171], v[208:211], v[22:25]
	v_mfma_f32_16x16x32_bf16 v[18:21], v[184:187], v[208:211], v[18:21]
	v_mfma_f32_16x16x32_bf16 v[6:9], v[168:171], v[216:219], v[6:9]
	v_mfma_f32_16x16x32_bf16 v[2:5], v[184:187], v[216:219], v[2:5]
	v_mfma_f32_16x16x32_bf16 v[54:57], v[172:175], v[196:199], v[54:57]
	v_mfma_f32_16x16x32_bf16 v[50:53], v[188:191], v[196:199], v[50:53]
	v_mfma_f32_16x16x32_bf16 v[38:41], v[172:175], v[204:207], v[38:41]
	v_mfma_f32_16x16x32_bf16 v[34:37], v[188:191], v[204:207], v[34:37]
	v_mfma_f32_16x16x32_bf16 v[22:25], v[172:175], v[212:215], v[22:25]
	v_mfma_f32_16x16x32_bf16 v[18:21], v[188:191], v[212:215], v[18:21]
	v_mfma_f32_16x16x32_bf16 v[6:9], v[172:175], v[220:223], v[6:9]
	v_mfma_f32_16x16x32_bf16 v[2:5], v[188:191], v[220:223], v[2:5]
	s_setprio 0
	s_barrier
	s_add_i32 s17, 0, 0x18000
	s_add_i32 s52, 0, 0x1c000
	v_add_u32_e32 v130, s17, v176
	v_add_u32_e32 v188, s52, v176
	ds_read_b128 v[114:117], v130
	ds_read_b128 v[118:121], v130 offset:1024
	ds_read_b128 v[126:129], v130 offset:2048
	ds_read_b128 v[130:133], v130 offset:3072
	ds_read_b128 v[168:171], v188
	ds_read_b128 v[172:175], v188 offset:1024
	ds_read_b128 v[184:187], v188 offset:2048
	ds_read_b128 v[188:191], v188 offset:3072
	s_add_u32 s18, s18, 0x40000
	s_addc_u32 s19, s19, 0
	s_mov_b32 m0, s65
	v_lshl_add_u64 v[232:233], s[18:19], 0, v[162:163]
	ds_read_b128 v[192:195], v183 offset:32768
	ds_read_b128 v[196:199], v183 offset:33792
	ds_read_b128 v[200:203], v183 offset:34816
	ds_read_b128 v[204:207], v183 offset:35840
	ds_read_b128 v[208:211], v183 offset:36864
	ds_read_b128 v[212:215], v183 offset:37888
	ds_read_b128 v[216:219], v183 offset:38912
	ds_read_b128 v[220:223], v183 offset:39936
	global_load_lds_dwordx4 v[232:233], off
	v_lshl_add_u64 v[232:233], s[18:19], 0, v[160:161]
	s_mov_b32 m0, s66
	s_nop 0
	global_load_lds_dwordx4 v[232:233], off
	s_waitcnt vmcnt(8)
	s_waitcnt lgkmcnt(0)
	s_barrier
	s_setprio 1
	v_mfma_f32_16x16x32_bf16 v[142:145], v[114:117], v[192:195], v[142:145]
	v_mfma_f32_16x16x32_bf16 v[138:141], v[126:129], v[192:195], v[138:141]
	v_mfma_f32_16x16x32_bf16 v[110:113], v[114:117], v[200:203], v[110:113]
	v_mfma_f32_16x16x32_bf16 v[106:109], v[126:129], v[200:203], v[106:109]
	v_mfma_f32_16x16x32_bf16 v[94:97], v[114:117], v[208:211], v[94:97]
	v_mfma_f32_16x16x32_bf16 v[90:93], v[126:129], v[208:211], v[90:93]
	v_mfma_f32_16x16x32_bf16 v[78:81], v[114:117], v[216:219], v[78:81]
	v_mfma_f32_16x16x32_bf16 v[74:77], v[126:129], v[216:219], v[74:77]
	v_mfma_f32_16x16x32_bf16 v[142:145], v[118:121], v[196:199], v[142:145]
	v_mfma_f32_16x16x32_bf16 v[138:141], v[130:133], v[196:199], v[138:141]
	v_mfma_f32_16x16x32_bf16 v[110:113], v[118:121], v[204:207], v[110:113]
	v_mfma_f32_16x16x32_bf16 v[106:109], v[130:133], v[204:207], v[106:109]
	v_mfma_f32_16x16x32_bf16 v[94:97], v[118:121], v[212:215], v[94:97]
	v_mfma_f32_16x16x32_bf16 v[90:93], v[130:133], v[212:215], v[90:93]
	v_mfma_f32_16x16x32_bf16 v[78:81], v[118:121], v[220:223], v[78:81]
	v_mfma_f32_16x16x32_bf16 v[74:77], v[130:133], v[220:223], v[74:77]
	v_mfma_f32_16x16x32_bf16 v[134:137], v[168:171], v[192:195], v[134:137]
	v_mfma_f32_16x16x32_bf16 v[122:125], v[184:187], v[192:195], v[122:125]
	v_mfma_f32_16x16x32_bf16 v[102:105], v[168:171], v[200:203], v[102:105]
	v_mfma_f32_16x16x32_bf16 v[98:101], v[184:187], v[200:203], v[98:101]
	v_mfma_f32_16x16x32_bf16 v[86:89], v[168:171], v[208:211], v[86:89]
	v_mfma_f32_16x16x32_bf16 v[82:85], v[184:187], v[208:211], v[82:85]
	v_mfma_f32_16x16x32_bf16 v[70:73], v[168:171], v[216:219], v[70:73]
	v_mfma_f32_16x16x32_bf16 v[66:69], v[184:187], v[216:219], v[66:69]
	v_mfma_f32_16x16x32_bf16 v[134:137], v[172:175], v[196:199], v[134:137]
	v_mfma_f32_16x16x32_bf16 v[122:125], v[188:191], v[196:199], v[122:125]
	v_mfma_f32_16x16x32_bf16 v[102:105], v[172:175], v[204:207], v[102:105]
	v_mfma_f32_16x16x32_bf16 v[98:101], v[188:191], v[204:207], v[98:101]
	v_mfma_f32_16x16x32_bf16 v[86:89], v[172:175], v[212:215], v[86:89]
	v_mfma_f32_16x16x32_bf16 v[82:85], v[188:191], v[212:215], v[82:85]
	v_mfma_f32_16x16x32_bf16 v[70:73], v[172:175], v[220:223], v[70:73]
	v_mfma_f32_16x16x32_bf16 v[66:69], v[188:191], v[220:223], v[66:69]
	s_setprio 0
	s_barrier
; #define PG8_STAGE(bufoff, gbase, voff) do { _Pragma("unroll") for (int _i = 0; _i < 2; ++_i) \
;         __builtin_amdgcn_global_load_lds((const unsigned*)((const char*)(gbase) + (voff)[_i]), (PG8_LAS unsigned*)(lds + (bufoff) + ldsw + _i * 8192), 16, 0, 0); } while (0)
; #define PG8_LDA(dst, b, h) do { _Pragma("unroll") for (int m = 0; m < 4; ++m) _Pragma("unroll") for (int k = 0; k < 2; ++k) dst[m][k] = *(const PG8_LAS bf16x8*)(lds + PG8_SA(b, h) + aoff + m * 2048 + k * 1024); } while (0)
; #define PG8_MMA(ai, bj, At, Bt) do { __builtin_amdgcn_s_setprio(1); _Pragma("unroll") for (int m = 0; m < 4; ++m) _Pragma("unroll") for (int n = 0; n < 2; ++n) _Pragma("unroll") for (int k = 0; k < 2; ++k) \
;         acc[ai][bj][m][n] = __builtin_amdgcn_mfma_f32_16x16x32_bf16(Bt[n][k], At[m][k], acc[ai][bj][m][n], 0, 0, 0); __builtin_amdgcn_s_setprio(0); } while (0)
; #define PG8_WAIT_V(n) asm volatile("s_waitcnt vmcnt(" #n ")" ::: "memory")
; #define PG8_WAIT_L(n) asm volatile("s_waitcnt lgkmcnt(" #n ")" ::: "memory")
; #define PG8_BAR __builtin_amdgcn_s_barrier()
; #define PG8_SCHED __builtin_amdgcn_sched_barrier(0)
; template <class Epi, class Sched, bool ALIGN_EPI = false, bool SP2 = false>
; __device__ __forceinline__ void gemm_phase(PG8_LAS unsigned char* lds, const Gemm g, const Sched& S, const Epi& E, int tid_in) {
;     ...
;         for (int t = 0; t < nt; t += 2) {
;             const bool last = (t == nt - 2);
;             const char* a1 = cA + (size_t)(t + 1) * kstep;
;             const char* a2 = last ? nA : cA + (size_t)(t + 2) * kstep; const char* b2 = last ? nB : cB + (size_t)(t + 2) * kstep;
;     ...
;             PG8_LDA(At, 1, 1); PG8_STAGE(PG8_SB(1, 0), b3, voffB); PG8_STAGE(PG8_SB(1, 1), b3 + hstep, voffB); PG8_STAGE(PG8_SA(1, 0), a3, voffA);
;             PG8_WAIT_V(8); PG8_WAIT_L(0); PG8_BAR; PG8_MMA(1, 0, At, B0); PG8_MMA(1, 1, At, B1); PG8_BAR; PG8_SCHED;
	s_add_i32 s17, s17, s62
	v_lshl_add_u64 v[224:225], v[224:225], 0, vcc
	s_mov_b32 m0, s17
	ds_read_b128 v[192:195], v183 offset:49152
	ds_read_b128 v[196:199], v183 offset:50176
	ds_read_b128 v[200:203], v183 offset:51200
	ds_read_b128 v[204:207], v183 offset:52224
	ds_read_b128 v[208:211], v183 offset:53248
	ds_read_b128 v[212:215], v183 offset:54272
	ds_read_b128 v[216:219], v183 offset:55296
	ds_read_b128 v[220:223], v183 offset:56320
	global_load_lds_dwordx4 v[224:225], off
	s_add_i32 m0, s17, 0x2000
	s_add_u32 s0, s0, 0x40080
	v_lshl_add_u64 v[224:225], v[226:227], 0, vcc
	s_addc_u32 s1, s1, 0
	s_add_i32 s17, s52, s62
	global_load_lds_dwordx4 v[224:225], off
	v_lshl_add_u64 v[224:225], s[0:1], 0, v[162:163]
	s_mov_b32 m0, s17
	s_nop 0
	global_load_lds_dwordx4 v[224:225], off
	v_lshl_add_u64 v[224:225], s[0:1], 0, v[160:161]
	s_add_i32 m0, s17, 0x2000
	s_nop 0
	global_load_lds_dwordx4 v[224:225], off
	v_lshl_add_u64 v[224:225], v[228:229], 0, vcc
	s_mov_b32 m0, s70
	s_nop 0
	global_load_lds_dwordx4 v[224:225], off
	v_lshl_add_u64 v[224:225], v[230:231], 0, vcc
	s_mov_b32 m0, s71
	s_nop 0
	global_load_lds_dwordx4 v[224:225], off
	s_waitcnt vmcnt(8)
	s_waitcnt lgkmcnt(0)
	s_barrier
	s_setprio 1
	v_mfma_f32_16x16x32_bf16 v[62:65], v[114:117], v[192:195], v[62:65]
	v_mfma_f32_16x16x32_bf16 v[58:61], v[126:129], v[192:195], v[58:61]
	v_mfma_f32_16x16x32_bf16 v[46:49], v[114:117], v[200:203], v[46:49]
	v_mfma_f32_16x16x32_bf16 v[42:45], v[126:129], v[200:203], v[42:45]
	v_mfma_f32_16x16x32_bf16 v[30:33], v[114:117], v[208:211], v[30:33]
	v_mfma_f32_16x16x32_bf16 v[26:29], v[126:129], v[208:211], v[26:29]
	v_mfma_f32_16x16x32_bf16 v[14:17], v[114:117], v[216:219], v[14:17]
	v_mfma_f32_16x16x32_bf16 v[10:13], v[126:129], v[216:219], v[10:13]
	v_mfma_f32_16x16x32_bf16 v[62:65], v[118:121], v[196:199], v[62:65]
	v_mfma_f32_16x16x32_bf16 v[58:61], v[130:133], v[196:199], v[58:61]
	v_mfma_f32_16x16x32_bf16 v[46:49], v[118:121], v[204:207], v[46:49]
	v_mfma_f32_16x16x32_bf16 v[42:45], v[130:133], v[204:207], v[42:45]
	v_mfma_f32_16x16x32_bf16 v[30:33], v[118:121], v[212:215], v[30:33]
	v_mfma_f32_16x16x32_bf16 v[26:29], v[130:133], v[212:215], v[26:29]
	v_mfma_f32_16x16x32_bf16 v[14:17], v[118:121], v[220:223], v[14:17]
	v_mfma_f32_16x16x32_bf16 v[10:13], v[130:133], v[220:223], v[10:13]
	v_mfma_f32_16x16x32_bf16 v[54:57], v[168:171], v[192:195], v[54:57]
	v_mfma_f32_16x16x32_bf16 v[50:53], v[184:187], v[192:195], v[50:53]
	v_mfma_f32_16x16x32_bf16 v[38:41], v[168:171], v[200:203], v[38:41]
	v_mfma_f32_16x16x32_bf16 v[34:37], v[184:187], v[200:203], v[34:37]
	v_mfma_f32_16x16x32_bf16 v[22:25], v[168:171], v[208:211], v[22:25]
	v_mfma_f32_16x16x32_bf16 v[18:21], v[184:187], v[208:211], v[18:21]
	v_mfma_f32_16x16x32_bf16 v[6:9], v[168:171], v[216:219], v[6:9]
	v_mfma_f32_16x16x32_bf16 v[2:5], v[184:187], v[216:219], v[2:5]
	v_mfma_f32_16x16x32_bf16 v[54:57], v[172:175], v[196:199], v[54:57]
	v_mfma_f32_16x16x32_bf16 v[50:53], v[188:191], v[196:199], v[50:53]
	v_mfma_f32_16x16x32_bf16 v[38:41], v[172:175], v[204:207], v[38:41]
	v_mfma_f32_16x16x32_bf16 v[34:37], v[188:191], v[204:207], v[34:37]
	v_mfma_f32_16x16x32_bf16 v[22:25], v[172:175], v[212:215], v[22:25]
	v_mfma_f32_16x16x32_bf16 v[18:21], v[188:191], v[212:215], v[18:21]
	v_mfma_f32_16x16x32_bf16 v[6:9], v[172:175], v[220:223], v[6:9]
	v_mfma_f32_16x16x32_bf16 v[2:5], v[188:191], v[220:223], v[2:5]
	s_setprio 0
	s_barrier
	s_add_i32 s94, s94, 2
	s_add_u32 s88, s88, 0x100
	s_addc_u32 s89, s89, 0
	s_cmp_gt_u32 s94, 13
	s_mov_b64 s[52:53], s[54:55]
	s_cbranch_scc0 .LBB0_855
	s_and_b64 vcc, exec, s[10:11]
	s_cbranch_vccz .LBB0_858
	s_barrier

; #define PG8_STAGE(bufoff, gbase, voff) do { _Pragma("unroll") for (int _i = 0; _i < 2; ++_i) \
;         __builtin_amdgcn_global_load_lds((const unsigned*)((const char*)(gbase) + (voff)[_i]), (PG8_LAS unsigned*)(lds + (bufoff) + ldsw + _i * 8192), 16, 0, 0); } while (0)
; #define PG8_LDA(dst, b, h) do { _Pragma("unroll") for (int m = 0; m < 4; ++m) _Pragma("unroll") for (int k = 0; k < 2; ++k) dst[m][k] = *(const PG8_LAS bf16x8*)(lds + PG8_SA(b, h) + aoff + m * 2048 + k * 1024); } while (0)
; #define PG8_LDB(dst, b, h) do { _Pragma("unroll") for (int n = 0; n < 2; ++n) _Pragma("unroll") for (int k = 0; k < 2; ++k) dst[n][k] = *(const PG8_LAS bf16x8*)(lds + PG8_SB(b, h) + boff + n * 2048 + k * 1024); } while (0)
; #define PG8_MMA(ai, bj, At, Bt) do { __builtin_amdgcn_s_setprio(1); _Pragma("unroll") for (int m = 0; m < 4; ++m) _Pragma("unroll") for (int n = 0; n < 2; ++n) _Pragma("unroll") for (int k = 0; k < 2; ++k) \
;         acc[ai][bj][m][n] = __builtin_amdgcn_mfma_f32_16x16x32_bf16(Bt[n][k], At[m][k], acc[ai][bj][m][n], 0, 0, 0); __builtin_amdgcn_s_setprio(0); } while (0)
; #define PG8_WAIT_V(n) asm volatile("s_waitcnt vmcnt(" #n ")" ::: "memory")
; #define PG8_WAIT_L(n) asm volatile("s_waitcnt lgkmcnt(" #n ")" ::: "memory")
; #define PG8_BAR __builtin_amdgcn_s_barrier()
; #define PG8_SCHED __builtin_amdgcn_sched_barrier(0)
; template <class Epi, class Sched, bool ALIGN_EPI = false, bool SP2 = false>
; __device__ __forceinline__ void gemm_phase(PG8_LAS unsigned char* lds, const Gemm g, const Sched& S, const Epi& E, int tid_in) {
;     ...
;         for (int t = 0; t < nt; t += 2) {
;             const bool last = (t == nt - 2);
;             const char* a1 = cA + (size_t)(t + 1) * kstep;
;             const char* a2 = last ? nA : cA + (size_t)(t + 2) * kstep; const char* b2 = last ? nB : cB + (size_t)(t + 2) * kstep;
;     ...
;             PG8_LDB(B0, 0, 0); PG8_LDB(B1, 0, 1); PG8_SCHED; PG8_LDA(At, 0, 0); PG8_STAGE(PG8_SA(1, 1), a1 + hstep, voffA);
;             PG8_WAIT_V(8); PG8_WAIT_L(0); PG8_BAR; PG8_MMA(0, 0, At, B0); PG8_MMA(0, 1, At, B1); PG8_BAR; PG8_SCHED;
;             PG8_LDA(At, 0, 1); PG8_STAGE(PG8_SB(0, 0), b2, voffB); PG8_STAGE(PG8_SB(0, 1), b2 + hstep, voffB); PG8_STAGE(PG8_SA(0, 0), a2, voffA);
.LBB0_1040:
	s_add_u32 s0, s48, 0xfffc0080
	s_addc_u32 s1, s49, -1
	s_add_i32 s17, 0, 0x10000
	s_cmp_eq_u32 s69, 12
	s_cselect_b32 s19, s13, s1
	s_cselect_b32 s18, s65, s0
	v_add_u32_e32 v163, s17, v160
	s_cselect_b32 s1, s11, s68
	s_cselect_b32 s0, s66, s67
	s_add_i32 s75, 0, 0x14000
	ds_read_b128 v[142:145], v163
	ds_read_b128 v[164:167], v163 offset:1024
	ds_read_b128 v[168:171], v163 offset:2048
	ds_read_b128 v[172:175], v163 offset:3072
	v_add_u32_e32 v163, s75, v160
	ds_read_b128 v[184:187], v163
	ds_read_b128 v[188:191], v163 offset:1024
	ds_read_b128 v[192:195], v163 offset:2048
	ds_read_b128 v[196:199], v163 offset:3072
	v_lshl_add_u64 v[176:177], s[48:49], 0, v[138:139]
	s_add_i32 m0, s55, 0xc000
	ds_read_b128 v[200:203], v162
	ds_read_b128 v[204:207], v162 offset:1024
	ds_read_b128 v[208:211], v162 offset:2048
	ds_read_b128 v[212:215], v162 offset:3072
	ds_read_b128 v[216:219], v162 offset:4096
	ds_read_b128 v[220:223], v162 offset:5120
	ds_read_b128 v[224:227], v162 offset:6144
	ds_read_b128 v[228:231], v162 offset:7168
	global_load_lds_dwordx4 v[176:177], off
	v_lshl_add_u64 v[176:177], s[48:49], 0, v[140:141]
	s_add_i32 m0, s55, 0xe000
	s_nop 0
	global_load_lds_dwordx4 v[176:177], off
	s_waitcnt vmcnt(8)
	s_waitcnt lgkmcnt(0)
	s_barrier
	s_setprio 1
	v_mfma_f32_16x16x32_bf16 v[126:129], v[142:145], v[200:203], v[126:129]
	v_mfma_f32_16x16x32_bf16 v[118:121], v[168:171], v[200:203], v[118:121]
	v_mfma_f32_16x16x32_bf16 v[110:113], v[142:145], v[208:211], v[110:113]
	v_mfma_f32_16x16x32_bf16 v[102:105], v[168:171], v[208:211], v[102:105]
	v_mfma_f32_16x16x32_bf16 v[94:97], v[142:145], v[216:219], v[94:97]
	v_mfma_f32_16x16x32_bf16 v[86:89], v[168:171], v[216:219], v[86:89]
	v_mfma_f32_16x16x32_bf16 v[78:81], v[142:145], v[224:227], v[78:81]
	v_mfma_f32_16x16x32_bf16 v[70:73], v[168:171], v[224:227], v[70:73]
	v_mfma_f32_16x16x32_bf16 v[126:129], v[164:167], v[204:207], v[126:129]
	v_mfma_f32_16x16x32_bf16 v[118:121], v[172:175], v[204:207], v[118:121]
	v_mfma_f32_16x16x32_bf16 v[110:113], v[164:167], v[212:215], v[110:113]
	v_mfma_f32_16x16x32_bf16 v[102:105], v[172:175], v[212:215], v[102:105]
	v_mfma_f32_16x16x32_bf16 v[94:97], v[164:167], v[220:223], v[94:97]
	v_mfma_f32_16x16x32_bf16 v[86:89], v[172:175], v[220:223], v[86:89]
	v_mfma_f32_16x16x32_bf16 v[78:81], v[164:167], v[228:231], v[78:81]
	v_mfma_f32_16x16x32_bf16 v[70:73], v[172:175], v[228:231], v[70:73]
	v_mfma_f32_16x16x32_bf16 v[122:125], v[184:187], v[200:203], v[122:125]
	v_mfma_f32_16x16x32_bf16 v[114:117], v[192:195], v[200:203], v[114:117]
	v_mfma_f32_16x16x32_bf16 v[106:109], v[184:187], v[208:211], v[106:109]
	v_mfma_f32_16x16x32_bf16 v[98:101], v[192:195], v[208:211], v[98:101]
	v_mfma_f32_16x16x32_bf16 v[90:93], v[184:187], v[216:219], v[90:93]
	v_mfma_f32_16x16x32_bf16 v[82:85], v[192:195], v[216:219], v[82:85]
	v_mfma_f32_16x16x32_bf16 v[74:77], v[184:187], v[224:227], v[74:77]
	v_mfma_f32_16x16x32_bf16 v[66:69], v[192:195], v[224:227], v[66:69]
	v_mfma_f32_16x16x32_bf16 v[122:125], v[188:191], v[204:207], v[122:125]
	v_mfma_f32_16x16x32_bf16 v[114:117], v[196:199], v[204:207], v[114:117]
	v_mfma_f32_16x16x32_bf16 v[106:109], v[188:191], v[212:215], v[106:109]
	v_mfma_f32_16x16x32_bf16 v[98:101], v[196:199], v[212:215], v[98:101]
	v_mfma_f32_16x16x32_bf16 v[90:93], v[188:191], v[220:223], v[90:93]
	v_mfma_f32_16x16x32_bf16 v[82:85], v[196:199], v[220:223], v[82:85]
	v_mfma_f32_16x16x32_bf16 v[74:77], v[188:191], v[228:231], v[74:77]
	v_mfma_f32_16x16x32_bf16 v[66:69], v[196:199], v[228:231], v[66:69]
	s_setprio 0
	s_barrier
	s_add_i32 s17, s17, s54
	v_lshl_add_u64 v[176:177], s[0:1], 0, v[134:135]
	s_mov_b32 m0, s17
	ds_read_b128 v[200:203], v162 offset:16384
	ds_read_b128 v[204:207], v162 offset:17408
	ds_read_b128 v[208:211], v162 offset:18432
	ds_read_b128 v[212:215], v162 offset:19456
	ds_read_b128 v[216:219], v162 offset:20480
	ds_read_b128 v[220:223], v162 offset:21504
	ds_read_b128 v[224:227], v162 offset:22528
	ds_read_b128 v[228:231], v162 offset:23552
	global_load_lds_dwordx4 v[176:177], off
	s_add_i32 m0, s17, 0x2000
	s_add_u32 s70, s0, 0x40000
	v_lshl_add_u64 v[232:233], s[0:1], 0, v[130:131]
	s_addc_u32 s71, s1, 0
	s_add_i32 s17, s75, s54
	global_load_lds_dwordx4 v[232:233], off
	v_lshl_add_u64 v[234:235], s[70:71], 0, v[134:135]
	s_mov_b32 m0, s17
	v_lshl_add_u64 v[236:237], s[18:19], 0, v[132:133]
	global_load_lds_dwordx4 v[234:235], off
	v_lshl_add_u64 v[234:235], s[70:71], 0, v[130:131]
	s_add_i32 m0, s17, 0x2000
	s_nop 0
	global_load_lds_dwordx4 v[234:235], off
	v_lshl_add_u64 v[234:235], s[18:19], 0, v[136:137]
	s_mov_b32 m0, s55
	s_nop 0
	global_load_lds_dwordx4 v[234:235], off
	s_mov_b32 m0, s58
	s_nop 0
	global_load_lds_dwordx4 v[236:237], off
	s_waitcnt vmcnt(8)
	s_waitcnt lgkmcnt(0)
	s_barrier
; #define PG8_STAGE(bufoff, gbase, voff) do { _Pragma("unroll") for (int _i = 0; _i < 2; ++_i) \
;         __builtin_amdgcn_global_load_lds((const unsigned*)((const char*)(gbase) + (voff)[_i]), (PG8_LAS unsigned*)(lds + (bufoff) + ldsw + _i * 8192), 16, 0, 0); } while (0)
; #define PG8_LDA(dst, b, h) do { _Pragma("unroll") for (int m = 0; m < 4; ++m) _Pragma("unroll") for (int k = 0; k < 2; ++k) dst[m][k] = *(const PG8_LAS bf16x8*)(lds + PG8_SA(b, h) + aoff + m * 2048 + k * 1024); } while (0)
; #define PG8_LDB(dst, b, h) do { _Pragma("unroll") for (int n = 0; n < 2; ++n) _Pragma("unroll") for (int k = 0; k < 2; ++k) dst[n][k] = *(const PG8_LAS bf16x8*)(lds + PG8_SB(b, h) + boff + n * 2048 + k * 1024); } while (0)
; #define PG8_MMA(ai, bj, At, Bt) do { __builtin_amdgcn_s_setprio(1); _Pragma("unroll") for (int m = 0; m < 4; ++m) _Pragma("unroll") for (int n = 0; n < 2; ++n) _Pragma("unroll") for (int k = 0; k < 2; ++k) \
;         acc[ai][bj][m][n] = __builtin_amdgcn_mfma_f32_16x16x32_bf16(Bt[n][k], At[m][k], acc[ai][bj][m][n], 0, 0, 0); __builtin_amdgcn_s_setprio(0); } while (0)
; #define PG8_WAIT_V(n) asm volatile("s_waitcnt vmcnt(" #n ")" ::: "memory")
; #define PG8_WAIT_L(n) asm volatile("s_waitcnt lgkmcnt(" #n ")" ::: "memory")
; #define PG8_BAR __builtin_amdgcn_s_barrier()
; #define PG8_SCHED __builtin_amdgcn_sched_barrier(0)
; template <class Epi, class Sched, bool ALIGN_EPI = false, bool SP2 = false>
; __device__ __forceinline__ void gemm_phase(PG8_LAS unsigned char* lds, const Gemm g, const Sched& S, const Epi& E, int tid_in) {
;     ...
;             PG8_WAIT_V(8); PG8_WAIT_L(0); PG8_BAR; PG8_MMA(1, 0, At, B0); PG8_MMA(1, 1, At, B1); PG8_BAR; PG8_SCHED;
;             PG8_LDB(B0, 1, 0); PG8_LDB(B1, 1, 1); PG8_SCHED; PG8_LDA(At, 1, 0); PG8_STAGE(PG8_SA(0, 1), a2 + hstep, voffA);
;             PG8_WAIT_V(8); PG8_WAIT_L(0); PG8_BAR; PG8_MMA(0, 0, At, B0); PG8_MMA(0, 1, At, B1); PG8_BAR; PG8_SCHED;
	s_setprio 1
	v_mfma_f32_16x16x32_bf16 v[62:65], v[142:145], v[200:203], v[62:65]
	v_mfma_f32_16x16x32_bf16 v[54:57], v[168:171], v[200:203], v[54:57]
	v_mfma_f32_16x16x32_bf16 v[46:49], v[142:145], v[208:211], v[46:49]
	v_mfma_f32_16x16x32_bf16 v[38:41], v[168:171], v[208:211], v[38:41]
	v_mfma_f32_16x16x32_bf16 v[30:33], v[142:145], v[216:219], v[30:33]
	v_mfma_f32_16x16x32_bf16 v[22:25], v[168:171], v[216:219], v[22:25]
	v_mfma_f32_16x16x32_bf16 v[14:17], v[142:145], v[224:227], v[14:17]
	v_mfma_f32_16x16x32_bf16 v[6:9], v[168:171], v[224:227], v[6:9]
	v_mfma_f32_16x16x32_bf16 v[62:65], v[164:167], v[204:207], v[62:65]
	v_mfma_f32_16x16x32_bf16 v[54:57], v[172:175], v[204:207], v[54:57]
	v_mfma_f32_16x16x32_bf16 v[46:49], v[164:167], v[212:215], v[46:49]
	v_mfma_f32_16x16x32_bf16 v[38:41], v[172:175], v[212:215], v[38:41]
	v_mfma_f32_16x16x32_bf16 v[30:33], v[164:167], v[220:223], v[30:33]
	v_mfma_f32_16x16x32_bf16 v[22:25], v[172:175], v[220:223], v[22:25]
	v_mfma_f32_16x16x32_bf16 v[14:17], v[164:167], v[228:231], v[14:17]
	v_mfma_f32_16x16x32_bf16 v[6:9], v[172:175], v[228:231], v[6:9]
	v_mfma_f32_16x16x32_bf16 v[58:61], v[184:187], v[200:203], v[58:61]
	v_mfma_f32_16x16x32_bf16 v[50:53], v[192:195], v[200:203], v[50:53]
	v_mfma_f32_16x16x32_bf16 v[42:45], v[184:187], v[208:211], v[42:45]
	v_mfma_f32_16x16x32_bf16 v[34:37], v[192:195], v[208:211], v[34:37]
	v_mfma_f32_16x16x32_bf16 v[26:29], v[184:187], v[216:219], v[26:29]
	v_mfma_f32_16x16x32_bf16 v[18:21], v[192:195], v[216:219], v[18:21]
	v_mfma_f32_16x16x32_bf16 v[10:13], v[184:187], v[224:227], v[10:13]
	v_mfma_f32_16x16x32_bf16 v[2:5], v[192:195], v[224:227], v[2:5]
	v_mfma_f32_16x16x32_bf16 v[58:61], v[188:191], v[204:207], v[58:61]
	v_mfma_f32_16x16x32_bf16 v[50:53], v[196:199], v[204:207], v[50:53]
	v_mfma_f32_16x16x32_bf16 v[42:45], v[188:191], v[212:215], v[42:45]
	v_mfma_f32_16x16x32_bf16 v[34:37], v[196:199], v[212:215], v[34:37]
	v_mfma_f32_16x16x32_bf16 v[26:29], v[188:191], v[220:223], v[26:29]
	v_mfma_f32_16x16x32_bf16 v[18:21], v[196:199], v[220:223], v[18:21]
	v_mfma_f32_16x16x32_bf16 v[10:13], v[188:191], v[228:231], v[10:13]
	v_mfma_f32_16x16x32_bf16 v[2:5], v[196:199], v[228:231], v[2:5]
	s_setprio 0
	s_barrier
	s_add_i32 s17, 0, 0x18000
	v_add_u32_e32 v163, s17, v160
	s_add_i32 s70, 0, 0x1c000
	ds_read_b128 v[142:145], v163
	ds_read_b128 v[164:167], v163 offset:1024
	ds_read_b128 v[168:171], v163 offset:2048
	ds_read_b128 v[172:175], v163 offset:3072
	v_add_u32_e32 v163, s70, v160
	ds_read_b128 v[184:187], v163
	ds_read_b128 v[188:191], v163 offset:1024
	ds_read_b128 v[192:195], v163 offset:2048
	ds_read_b128 v[196:199], v163 offset:3072
	s_add_u32 s18, s18, 0x40000
	s_addc_u32 s19, s19, 0
	s_mov_b32 m0, s59
	v_lshl_add_u64 v[238:239], s[18:19], 0, v[136:137]
	ds_read_b128 v[200:203], v162 offset:32768
	ds_read_b128 v[204:207], v162 offset:33792
	ds_read_b128 v[208:211], v162 offset:34816
	ds_read_b128 v[212:215], v162 offset:35840
	ds_read_b128 v[216:219], v162 offset:36864
	ds_read_b128 v[220:223], v162 offset:37888
	ds_read_b128 v[224:227], v162 offset:38912
	ds_read_b128 v[228:231], v162 offset:39936
	global_load_lds_dwordx4 v[238:239], off
	v_lshl_add_u64 v[238:239], s[18:19], 0, v[132:133]
	s_mov_b32 m0, s60
	s_nop 0
	global_load_lds_dwordx4 v[238:239], off
	s_waitcnt vmcnt(8)
	s_waitcnt lgkmcnt(0)
	s_barrier
	s_setprio 1
	v_mfma_f32_16x16x32_bf16 v[126:129], v[142:145], v[200:203], v[126:129]
	v_mfma_f32_16x16x32_bf16 v[118:121], v[168:171], v[200:203], v[118:121]
	v_mfma_f32_16x16x32_bf16 v[110:113], v[142:145], v[208:211], v[110:113]
	v_mfma_f32_16x16x32_bf16 v[102:105], v[168:171], v[208:211], v[102:105]
	v_mfma_f32_16x16x32_bf16 v[94:97], v[142:145], v[216:219], v[94:97]
	v_mfma_f32_16x16x32_bf16 v[86:89], v[168:171], v[216:219], v[86:89]
	v_mfma_f32_16x16x32_bf16 v[78:81], v[142:145], v[224:227], v[78:81]
	v_mfma_f32_16x16x32_bf16 v[70:73], v[168:171], v[224:227], v[70:73]
	v_mfma_f32_16x16x32_bf16 v[126:129], v[164:167], v[204:207], v[126:129]
	v_mfma_f32_16x16x32_bf16 v[118:121], v[172:175], v[204:207], v[118:121]
	v_mfma_f32_16x16x32_bf16 v[110:113], v[164:167], v[212:215], v[110:113]
	v_mfma_f32_16x16x32_bf16 v[102:105], v[172:175], v[212:215], v[102:105]
	v_mfma_f32_16x16x32_bf16 v[94:97], v[164:167], v[220:223], v[94:97]
	v_mfma_f32_16x16x32_bf16 v[86:89], v[172:175], v[220:223], v[86:89]
	v_mfma_f32_16x16x32_bf16 v[78:81], v[164:167], v[228:231], v[78:81]
	v_mfma_f32_16x16x32_bf16 v[70:73], v[172:175], v[228:231], v[70:73]
	v_mfma_f32_16x16x32_bf16 v[122:125], v[184:187], v[200:203], v[122:125]
	v_mfma_f32_16x16x32_bf16 v[114:117], v[192:195], v[200:203], v[114:117]
	v_mfma_f32_16x16x32_bf16 v[106:109], v[184:187], v[208:211], v[106:109]
	v_mfma_f32_16x16x32_bf16 v[98:101], v[192:195], v[208:211], v[98:101]
	v_mfma_f32_16x16x32_bf16 v[90:93], v[184:187], v[216:219], v[90:93]
	v_mfma_f32_16x16x32_bf16 v[82:85], v[192:195], v[216:219], v[82:85]
	v_mfma_f32_16x16x32_bf16 v[74:77], v[184:187], v[224:227], v[74:77]
	v_mfma_f32_16x16x32_bf16 v[66:69], v[192:195], v[224:227], v[66:69]
	v_mfma_f32_16x16x32_bf16 v[122:125], v[188:191], v[204:207], v[122:125]
	v_mfma_f32_16x16x32_bf16 v[114:117], v[196:199], v[204:207], v[114:117]
	v_mfma_f32_16x16x32_bf16 v[106:109], v[188:191], v[212:215], v[106:109]
	v_mfma_f32_16x16x32_bf16 v[98:101], v[196:199], v[212:215], v[98:101]
	v_mfma_f32_16x16x32_bf16 v[90:93], v[188:191], v[220:223], v[90:93]
	v_mfma_f32_16x16x32_bf16 v[82:85], v[196:199], v[220:223], v[82:85]
	v_mfma_f32_16x16x32_bf16 v[74:77], v[188:191], v[228:231], v[74:77]
	v_mfma_f32_16x16x32_bf16 v[66:69], v[196:199], v[228:231], v[66:69]
	s_setprio 0
	s_barrier
; #define PG8_STAGE(bufoff, gbase, voff) do { _Pragma("unroll") for (int _i = 0; _i < 2; ++_i) \
;         __builtin_amdgcn_global_load_lds((const unsigned*)((const char*)(gbase) + (voff)[_i]), (PG8_LAS unsigned*)(lds + (bufoff) + ldsw + _i * 8192), 16, 0, 0); } while (0)
; #define PG8_LDA(dst, b, h) do { _Pragma("unroll") for (int m = 0; m < 4; ++m) _Pragma("unroll") for (int k = 0; k < 2; ++k) dst[m][k] = *(const PG8_LAS bf16x8*)(lds + PG8_SA(b, h) + aoff + m * 2048 + k * 1024); } while (0)
; #define PG8_MMA(ai, bj, At, Bt) do { __builtin_amdgcn_s_setprio(1); _Pragma("unroll") for (int m = 0; m < 4; ++m) _Pragma("unroll") for (int n = 0; n < 2; ++n) _Pragma("unroll") for (int k = 0; k < 2; ++k) \
;         acc[ai][bj][m][n] = __builtin_amdgcn_mfma_f32_16x16x32_bf16(Bt[n][k], At[m][k], acc[ai][bj][m][n], 0, 0, 0); __builtin_amdgcn_s_setprio(0); } while (0)
; #define PG8_WAIT_V(n) asm volatile("s_waitcnt vmcnt(" #n ")" ::: "memory")
; #define PG8_WAIT_L(n) asm volatile("s_waitcnt lgkmcnt(" #n ")" ::: "memory")
; #define PG8_BAR __builtin_amdgcn_s_barrier()
; #define PG8_SCHED __builtin_amdgcn_sched_barrier(0)
; template <class Epi, class Sched, bool ALIGN_EPI = false, bool SP2 = false>
; __device__ __forceinline__ void gemm_phase(PG8_LAS unsigned char* lds, const Gemm g, const Sched& S, const Epi& E, int tid_in) {
;     ...
;         for (int t = 0; t < nt; t += 2) {
;             const bool last = (t == nt - 2);
;             const char* a1 = cA + (size_t)(t + 1) * kstep;
;             const char* a2 = last ? nA : cA + (size_t)(t + 2) * kstep; const char* b2 = last ? nB : cB + (size_t)(t + 2) * kstep;
;     ...
;             PG8_LDA(At, 1, 1); PG8_STAGE(PG8_SB(1, 0), b3, voffB); PG8_STAGE(PG8_SB(1, 1), b3 + hstep, voffB); PG8_STAGE(PG8_SA(1, 0), a3, voffA);
;             PG8_WAIT_V(8); PG8_WAIT_L(0); PG8_BAR; PG8_MMA(1, 0, At, B0); PG8_MMA(1, 1, At, B1); PG8_BAR; PG8_SCHED;
	s_add_i32 s17, s17, s54
	v_lshl_add_u64 v[176:177], v[176:177], 0, s[94:95]
	s_mov_b32 m0, s17
	ds_read_b128 v[200:203], v162 offset:49152
	ds_read_b128 v[204:207], v162 offset:50176
	ds_read_b128 v[208:211], v162 offset:51200
	ds_read_b128 v[212:215], v162 offset:52224
	ds_read_b128 v[216:219], v162 offset:53248
	ds_read_b128 v[220:223], v162 offset:54272
	ds_read_b128 v[224:227], v162 offset:55296
	ds_read_b128 v[228:231], v162 offset:56320
	global_load_lds_dwordx4 v[176:177], off
	s_add_i32 m0, s17, 0x2000
	s_add_u32 s0, s0, 0x40080
	v_lshl_add_u64 v[176:177], v[232:233], 0, s[94:95]
	s_addc_u32 s1, s1, 0
	s_add_i32 s17, s70, s54
	global_load_lds_dwordx4 v[176:177], off
	v_lshl_add_u64 v[176:177], s[0:1], 0, v[134:135]
	s_mov_b32 m0, s17
	s_nop 0
	global_load_lds_dwordx4 v[176:177], off
	v_lshl_add_u64 v[176:177], s[0:1], 0, v[130:131]
	s_add_i32 m0, s17, 0x2000
	s_nop 0
	global_load_lds_dwordx4 v[176:177], off
	v_lshl_add_u64 v[176:177], v[234:235], 0, s[94:95]
	s_mov_b32 m0, s61
	s_nop 0
	global_load_lds_dwordx4 v[176:177], off
	v_lshl_add_u64 v[176:177], v[236:237], 0, s[94:95]
	s_mov_b32 m0, s62
	s_nop 0
	global_load_lds_dwordx4 v[176:177], off
	s_waitcnt vmcnt(8)
	s_waitcnt lgkmcnt(0)
	s_barrier
	s_setprio 1
	v_mfma_f32_16x16x32_bf16 v[62:65], v[142:145], v[200:203], v[62:65]
	v_mfma_f32_16x16x32_bf16 v[54:57], v[168:171], v[200:203], v[54:57]
	v_mfma_f32_16x16x32_bf16 v[46:49], v[142:145], v[208:211], v[46:49]
	v_mfma_f32_16x16x32_bf16 v[38:41], v[168:171], v[208:211], v[38:41]
	v_mfma_f32_16x16x32_bf16 v[30:33], v[142:145], v[216:219], v[30:33]
	v_mfma_f32_16x16x32_bf16 v[22:25], v[168:171], v[216:219], v[22:25]
	v_mfma_f32_16x16x32_bf16 v[14:17], v[142:145], v[224:227], v[14:17]
	v_mfma_f32_16x16x32_bf16 v[6:9], v[168:171], v[224:227], v[6:9]
	v_mfma_f32_16x16x32_bf16 v[62:65], v[164:167], v[204:207], v[62:65]
	v_mfma_f32_16x16x32_bf16 v[54:57], v[172:175], v[204:207], v[54:57]
	v_mfma_f32_16x16x32_bf16 v[46:49], v[164:167], v[212:215], v[46:49]
	v_mfma_f32_16x16x32_bf16 v[38:41], v[172:175], v[212:215], v[38:41]
	v_mfma_f32_16x16x32_bf16 v[30:33], v[164:167], v[220:223], v[30:33]
	v_mfma_f32_16x16x32_bf16 v[22:25], v[172:175], v[220:223], v[22:25]
	v_mfma_f32_16x16x32_bf16 v[14:17], v[164:167], v[228:231], v[14:17]
	v_mfma_f32_16x16x32_bf16 v[6:9], v[172:175], v[228:231], v[6:9]
	v_mfma_f32_16x16x32_bf16 v[58:61], v[184:187], v[200:203], v[58:61]
	v_mfma_f32_16x16x32_bf16 v[50:53], v[192:195], v[200:203], v[50:53]
	v_mfma_f32_16x16x32_bf16 v[42:45], v[184:187], v[208:211], v[42:45]
	v_mfma_f32_16x16x32_bf16 v[34:37], v[192:195], v[208:211], v[34:37]
	v_mfma_f32_16x16x32_bf16 v[26:29], v[184:187], v[216:219], v[26:29]
	v_mfma_f32_16x16x32_bf16 v[18:21], v[192:195], v[216:219], v[18:21]
	v_mfma_f32_16x16x32_bf16 v[10:13], v[184:187], v[224:227], v[10:13]
	v_mfma_f32_16x16x32_bf16 v[2:5], v[192:195], v[224:227], v[2:5]
	v_mfma_f32_16x16x32_bf16 v[58:61], v[188:191], v[204:207], v[58:61]
	v_mfma_f32_16x16x32_bf16 v[50:53], v[196:199], v[204:207], v[50:53]
	v_mfma_f32_16x16x32_bf16 v[42:45], v[188:191], v[212:215], v[42:45]
	v_mfma_f32_16x16x32_bf16 v[34:37], v[196:199], v[212:215], v[34:37]
	v_mfma_f32_16x16x32_bf16 v[26:29], v[188:191], v[220:223], v[26:29]
	v_mfma_f32_16x16x32_bf16 v[18:21], v[196:199], v[220:223], v[18:21]
	v_mfma_f32_16x16x32_bf16 v[10:13], v[188:191], v[228:231], v[10:13]
	v_mfma_f32_16x16x32_bf16 v[2:5], v[196:199], v[228:231], v[2:5]
	s_setprio 0
	s_barrier
	s_add_i32 s69, s69, 2
	s_add_u32 s48, s48, 0x100
	s_addc_u32 s49, s49, 0
	s_add_u32 s67, s67, 0x100
	s_addc_u32 s68, s68, 0
	s_cmp_gt_u32 s69, 13
	s_cbranch_scc0 .LBB0_1040
	s_and_b64 vcc, exec, s[8:9]
	s_cbranch_vccz .LBB0_1043
	s_barrier

; #define PG8_STAGE(bufoff, gbase, voff) do { _Pragma("unroll") for (int _i = 0; _i < 2; ++_i) \
;         __builtin_amdgcn_global_load_lds((const unsigned*)((const char*)(gbase) + (voff)[_i]), (PG8_LAS unsigned*)(lds + (bufoff) + ldsw + _i * 8192), 16, 0, 0); } while (0)
; #define PG8_LDA(dst, b, h) do { _Pragma("unroll") for (int m = 0; m < 4; ++m) _Pragma("unroll") for (int k = 0; k < 2; ++k) dst[m][k] = *(const PG8_LAS bf16x8*)(lds + PG8_SA(b, h) + aoff + m * 2048 + k * 1024); } while (0)
; #define PG8_LDB(dst, b, h) do { _Pragma("unroll") for (int n = 0; n < 2; ++n) _Pragma("unroll") for (int k = 0; k < 2; ++k) dst[n][k] = *(const PG8_LAS bf16x8*)(lds + PG8_SB(b, h) + boff + n * 2048 + k * 1024); } while (0)
; #define PG8_MMA(ai, bj, At, Bt) do { __builtin_amdgcn_s_setprio(1); _Pragma("unroll") for (int m = 0; m < 4; ++m) _Pragma("unroll") for (int n = 0; n < 2; ++n) _Pragma("unroll") for (int k = 0; k < 2; ++k) \
;         acc[ai][bj][m][n] = __builtin_amdgcn_mfma_f32_16x16x32_bf16(Bt[n][k], At[m][k], acc[ai][bj][m][n], 0, 0, 0); __builtin_amdgcn_s_setprio(0); } while (0)
; #define PG8_WAIT_V(n) asm volatile("s_waitcnt vmcnt(" #n ")" ::: "memory")
; #define PG8_WAIT_L(n) asm volatile("s_waitcnt lgkmcnt(" #n ")" ::: "memory")
; #define PG8_BAR __builtin_amdgcn_s_barrier()
; #define PG8_SCHED __builtin_amdgcn_sched_barrier(0)
; template <class Epi, class Sched, bool ALIGN_EPI = false, bool SP2 = false>
; __device__ __forceinline__ void gemm_phase(PG8_LAS unsigned char* lds, const Gemm g, const Sched& S, const Epi& E, int tid_in) {
;     ...
;         for (int t = 0; t < nt; t += 2) {
;             const bool last = (t == nt - 2);
;             const char* a1 = cA + (size_t)(t + 1) * kstep;
;             const char* a2 = last ? nA : cA + (size_t)(t + 2) * kstep; const char* b2 = last ? nB : cB + (size_t)(t + 2) * kstep;
;     ...
;             PG8_LDB(B0, 0, 0); PG8_LDB(B1, 0, 1); PG8_SCHED; PG8_LDA(At, 0, 0); PG8_STAGE(PG8_SA(1, 1), a1 + hstep, voffA);
;             PG8_WAIT_V(8); PG8_WAIT_L(0); PG8_BAR; PG8_MMA(0, 0, At, B0); PG8_MMA(0, 1, At, B1); PG8_BAR; PG8_SCHED;
;             PG8_LDA(At, 0, 1); PG8_STAGE(PG8_SB(0, 0), b2, voffB); PG8_STAGE(PG8_SB(0, 1), b2 + hstep, voffB); PG8_STAGE(PG8_SA(0, 0), a2, voffA);
.LBB0_1115:
	s_add_u32 s44, s40, 0x100
	s_addc_u32 s45, s41, 0
	s_add_i32 s17, 0, 0x10000
	s_cmp_eq_u32 s69, 40
	s_cselect_b32 s19, s11, s45
	s_cselect_b32 s18, s10, s44
	s_cselect_b32 s1, s13, s68
	s_cselect_b32 s0, s12, s67
	s_add_i32 s70, 0, 0x14000
	v_add_u32_e32 v130, s17, v176
	v_add_u32_e32 v188, s70, v176
	ds_read_b128 v[114:117], v130
	ds_read_b128 v[118:121], v130 offset:1024
	ds_read_b128 v[126:129], v130 offset:2048
	ds_read_b128 v[130:133], v130 offset:3072
	ds_read_b128 v[168:171], v188
	ds_read_b128 v[172:175], v188 offset:1024
	ds_read_b128 v[184:187], v188 offset:2048
	ds_read_b128 v[188:191], v188 offset:3072
	v_lshl_add_u64 v[224:225], s[40:41], 0, v[164:165]
	s_add_i32 m0, s55, 0xc000
	ds_read_b128 v[192:195], v183
	ds_read_b128 v[196:199], v183 offset:1024
	ds_read_b128 v[200:203], v183 offset:2048
	ds_read_b128 v[204:207], v183 offset:3072
	ds_read_b128 v[208:211], v183 offset:4096
	ds_read_b128 v[212:215], v183 offset:5120
	ds_read_b128 v[216:219], v183 offset:6144
	ds_read_b128 v[220:223], v183 offset:7168
	global_load_lds_dwordx4 v[224:225], off
	v_lshl_add_u64 v[224:225], s[40:41], 0, v[166:167]
	s_add_i32 m0, s55, 0xe000
	s_nop 0
	global_load_lds_dwordx4 v[224:225], off
	s_waitcnt vmcnt(8)
	s_waitcnt lgkmcnt(0)
	s_barrier
	s_setprio 1
	v_mfma_f32_16x16x32_bf16 v[142:145], v[114:117], v[192:195], v[142:145]
	v_mfma_f32_16x16x32_bf16 v[138:141], v[126:129], v[192:195], v[138:141]
	v_mfma_f32_16x16x32_bf16 v[110:113], v[114:117], v[200:203], v[110:113]
	v_mfma_f32_16x16x32_bf16 v[106:109], v[126:129], v[200:203], v[106:109]
	v_mfma_f32_16x16x32_bf16 v[94:97], v[114:117], v[208:211], v[94:97]
	v_mfma_f32_16x16x32_bf16 v[90:93], v[126:129], v[208:211], v[90:93]
	v_mfma_f32_16x16x32_bf16 v[78:81], v[114:117], v[216:219], v[78:81]
	v_mfma_f32_16x16x32_bf16 v[74:77], v[126:129], v[216:219], v[74:77]
	v_mfma_f32_16x16x32_bf16 v[142:145], v[118:121], v[196:199], v[142:145]
	v_mfma_f32_16x16x32_bf16 v[138:141], v[130:133], v[196:199], v[138:141]
	v_mfma_f32_16x16x32_bf16 v[110:113], v[118:121], v[204:207], v[110:113]
	v_mfma_f32_16x16x32_bf16 v[106:109], v[130:133], v[204:207], v[106:109]
	v_mfma_f32_16x16x32_bf16 v[94:97], v[118:121], v[212:215], v[94:97]
	v_mfma_f32_16x16x32_bf16 v[90:93], v[130:133], v[212:215], v[90:93]
	v_mfma_f32_16x16x32_bf16 v[78:81], v[118:121], v[220:223], v[78:81]
	v_mfma_f32_16x16x32_bf16 v[74:77], v[130:133], v[220:223], v[74:77]
	v_mfma_f32_16x16x32_bf16 v[134:137], v[168:171], v[192:195], v[134:137]
	v_mfma_f32_16x16x32_bf16 v[122:125], v[184:187], v[192:195], v[122:125]
	v_mfma_f32_16x16x32_bf16 v[102:105], v[168:171], v[200:203], v[102:105]
	v_mfma_f32_16x16x32_bf16 v[98:101], v[184:187], v[200:203], v[98:101]
	v_mfma_f32_16x16x32_bf16 v[86:89], v[168:171], v[208:211], v[86:89]
	v_mfma_f32_16x16x32_bf16 v[82:85], v[184:187], v[208:211], v[82:85]
	v_mfma_f32_16x16x32_bf16 v[70:73], v[168:171], v[216:219], v[70:73]
	v_mfma_f32_16x16x32_bf16 v[66:69], v[184:187], v[216:219], v[66:69]
	v_mfma_f32_16x16x32_bf16 v[134:137], v[172:175], v[196:199], v[134:137]
	v_mfma_f32_16x16x32_bf16 v[122:125], v[188:191], v[196:199], v[122:125]
	v_mfma_f32_16x16x32_bf16 v[102:105], v[172:175], v[204:207], v[102:105]
	v_mfma_f32_16x16x32_bf16 v[98:101], v[188:191], v[204:207], v[98:101]
	v_mfma_f32_16x16x32_bf16 v[86:89], v[172:175], v[212:215], v[86:89]
	v_mfma_f32_16x16x32_bf16 v[82:85], v[188:191], v[212:215], v[82:85]
	v_mfma_f32_16x16x32_bf16 v[70:73], v[172:175], v[220:223], v[70:73]
	v_mfma_f32_16x16x32_bf16 v[66:69], v[188:191], v[220:223], v[66:69]
	s_setprio 0
	s_barrier
	s_add_i32 s17, s17, s54
	v_lshl_add_u64 v[224:225], s[0:1], 0, v[162:163]
	s_mov_b32 m0, s17
	ds_read_b128 v[192:195], v183 offset:16384
	ds_read_b128 v[196:199], v183 offset:17408
	ds_read_b128 v[200:203], v183 offset:18432
	ds_read_b128 v[204:207], v183 offset:19456
	ds_read_b128 v[208:211], v183 offset:20480
	ds_read_b128 v[212:215], v183 offset:21504
	ds_read_b128 v[216:219], v183 offset:22528
	ds_read_b128 v[220:223], v183 offset:23552
	global_load_lds_dwordx4 v[224:225], off
	s_add_i32 m0, s17, 0x2000
	s_add_u32 s40, s0, 0xb0000
	v_lshl_add_u64 v[226:227], s[0:1], 0, v[160:161]
	s_addc_u32 s41, s1, 0
	s_add_i32 s17, s70, s54
	global_load_lds_dwordx4 v[226:227], off
	v_lshl_add_u64 v[228:229], s[40:41], 0, v[162:163]
	s_mov_b32 m0, s17
	v_lshl_add_u64 v[230:231], s[18:19], 0, v[160:161]
	global_load_lds_dwordx4 v[228:229], off
	v_lshl_add_u64 v[228:229], s[40:41], 0, v[160:161]
	s_add_i32 m0, s17, 0x2000
	s_nop 0
	global_load_lds_dwordx4 v[228:229], off
	v_lshl_add_u64 v[228:229], s[18:19], 0, v[162:163]
	s_mov_b32 m0, s55
	s_nop 0
	global_load_lds_dwordx4 v[228:229], off
	s_mov_b32 m0, s58
	s_nop 0
	global_load_lds_dwordx4 v[230:231], off
	s_waitcnt vmcnt(8)
	s_waitcnt lgkmcnt(0)
	s_barrier
; #define PG8_STAGE(bufoff, gbase, voff) do { _Pragma("unroll") for (int _i = 0; _i < 2; ++_i) \
;         __builtin_amdgcn_global_load_lds((const unsigned*)((const char*)(gbase) + (voff)[_i]), (PG8_LAS unsigned*)(lds + (bufoff) + ldsw + _i * 8192), 16, 0, 0); } while (0)
; #define PG8_LDA(dst, b, h) do { _Pragma("unroll") for (int m = 0; m < 4; ++m) _Pragma("unroll") for (int k = 0; k < 2; ++k) dst[m][k] = *(const PG8_LAS bf16x8*)(lds + PG8_SA(b, h) + aoff + m * 2048 + k * 1024); } while (0)
; #define PG8_LDB(dst, b, h) do { _Pragma("unroll") for (int n = 0; n < 2; ++n) _Pragma("unroll") for (int k = 0; k < 2; ++k) dst[n][k] = *(const PG8_LAS bf16x8*)(lds + PG8_SB(b, h) + boff + n * 2048 + k * 1024); } while (0)
; #define PG8_MMA(ai, bj, At, Bt) do { __builtin_amdgcn_s_setprio(1); _Pragma("unroll") for (int m = 0; m < 4; ++m) _Pragma("unroll") for (int n = 0; n < 2; ++n) _Pragma("unroll") for (int k = 0; k < 2; ++k) \
;         acc[ai][bj][m][n] = __builtin_amdgcn_mfma_f32_16x16x32_bf16(Bt[n][k], At[m][k], acc[ai][bj][m][n], 0, 0, 0); __builtin_amdgcn_s_setprio(0); } while (0)
; #define PG8_WAIT_V(n) asm volatile("s_waitcnt vmcnt(" #n ")" ::: "memory")
; #define PG8_WAIT_L(n) asm volatile("s_waitcnt lgkmcnt(" #n ")" ::: "memory")
; #define PG8_BAR __builtin_amdgcn_s_barrier()
; #define PG8_SCHED __builtin_amdgcn_sched_barrier(0)
; template <class Epi, class Sched, bool ALIGN_EPI = false, bool SP2 = false>
; __device__ __forceinline__ void gemm_phase(PG8_LAS unsigned char* lds, const Gemm g, const Sched& S, const Epi& E, int tid_in) {
;     ...
;             PG8_WAIT_V(8); PG8_WAIT_L(0); PG8_BAR; PG8_MMA(1, 0, At, B0); PG8_MMA(1, 1, At, B1); PG8_BAR; PG8_SCHED;
;             PG8_LDB(B0, 1, 0); PG8_LDB(B1, 1, 1); PG8_SCHED; PG8_LDA(At, 1, 0); PG8_STAGE(PG8_SA(0, 1), a2 + hstep, voffA);
;             PG8_WAIT_V(8); PG8_WAIT_L(0); PG8_BAR; PG8_MMA(0, 0, At, B0); PG8_MMA(0, 1, At, B1); PG8_BAR; PG8_SCHED;
	s_setprio 1
	v_mfma_f32_16x16x32_bf16 v[62:65], v[114:117], v[192:195], v[62:65]
	v_mfma_f32_16x16x32_bf16 v[58:61], v[126:129], v[192:195], v[58:61]
	v_mfma_f32_16x16x32_bf16 v[46:49], v[114:117], v[200:203], v[46:49]
	v_mfma_f32_16x16x32_bf16 v[42:45], v[126:129], v[200:203], v[42:45]
	v_mfma_f32_16x16x32_bf16 v[30:33], v[114:117], v[208:211], v[30:33]
	v_mfma_f32_16x16x32_bf16 v[26:29], v[126:129], v[208:211], v[26:29]
	v_mfma_f32_16x16x32_bf16 v[14:17], v[114:117], v[216:219], v[14:17]
	v_mfma_f32_16x16x32_bf16 v[10:13], v[126:129], v[216:219], v[10:13]
	v_mfma_f32_16x16x32_bf16 v[62:65], v[118:121], v[196:199], v[62:65]
	v_mfma_f32_16x16x32_bf16 v[58:61], v[130:133], v[196:199], v[58:61]
	v_mfma_f32_16x16x32_bf16 v[46:49], v[118:121], v[204:207], v[46:49]
	v_mfma_f32_16x16x32_bf16 v[42:45], v[130:133], v[204:207], v[42:45]
	v_mfma_f32_16x16x32_bf16 v[30:33], v[118:121], v[212:215], v[30:33]
	v_mfma_f32_16x16x32_bf16 v[26:29], v[130:133], v[212:215], v[26:29]
	v_mfma_f32_16x16x32_bf16 v[14:17], v[118:121], v[220:223], v[14:17]
	v_mfma_f32_16x16x32_bf16 v[10:13], v[130:133], v[220:223], v[10:13]
	v_mfma_f32_16x16x32_bf16 v[54:57], v[168:171], v[192:195], v[54:57]
	v_mfma_f32_16x16x32_bf16 v[50:53], v[184:187], v[192:195], v[50:53]
	v_mfma_f32_16x16x32_bf16 v[38:41], v[168:171], v[200:203], v[38:41]
	v_mfma_f32_16x16x32_bf16 v[34:37], v[184:187], v[200:203], v[34:37]
	v_mfma_f32_16x16x32_bf16 v[22:25], v[168:171], v[208:211], v[22:25]
	v_mfma_f32_16x16x32_bf16 v[18:21], v[184:187], v[208:211], v[18:21]
	v_mfma_f32_16x16x32_bf16 v[6:9], v[168:171], v[216:219], v[6:9]
	v_mfma_f32_16x16x32_bf16 v[2:5], v[184:187], v[216:219], v[2:5]
	v_mfma_f32_16x16x32_bf16 v[54:57], v[172:175], v[196:199], v[54:57]
	v_mfma_f32_16x16x32_bf16 v[50:53], v[188:191], v[196:199], v[50:53]
	v_mfma_f32_16x16x32_bf16 v[38:41], v[172:175], v[204:207], v[38:41]
	v_mfma_f32_16x16x32_bf16 v[34:37], v[188:191], v[204:207], v[34:37]
	v_mfma_f32_16x16x32_bf16 v[22:25], v[172:175], v[212:215], v[22:25]
	v_mfma_f32_16x16x32_bf16 v[18:21], v[188:191], v[212:215], v[18:21]
	v_mfma_f32_16x16x32_bf16 v[6:9], v[172:175], v[220:223], v[6:9]
	v_mfma_f32_16x16x32_bf16 v[2:5], v[188:191], v[220:223], v[2:5]
	s_setprio 0
	s_barrier
	s_add_i32 s17, 0, 0x18000
	s_add_i32 s40, 0, 0x1c000
	v_add_u32_e32 v130, s17, v176
	v_add_u32_e32 v188, s40, v176
	ds_read_b128 v[114:117], v130
	ds_read_b128 v[118:121], v130 offset:1024
	ds_read_b128 v[126:129], v130 offset:2048
	ds_read_b128 v[130:133], v130 offset:3072
	ds_read_b128 v[168:171], v188
	ds_read_b128 v[172:175], v188 offset:1024
	ds_read_b128 v[184:187], v188 offset:2048
	ds_read_b128 v[188:191], v188 offset:3072
	s_add_u32 s18, s18, 0xb0000
	s_addc_u32 s19, s19, 0
	s_mov_b32 m0, s59
	v_lshl_add_u64 v[232:233], s[18:19], 0, v[162:163]
	ds_read_b128 v[192:195], v183 offset:32768
	ds_read_b128 v[196:199], v183 offset:33792
	ds_read_b128 v[200:203], v183 offset:34816
	ds_read_b128 v[204:207], v183 offset:35840
	ds_read_b128 v[208:211], v183 offset:36864
	ds_read_b128 v[212:215], v183 offset:37888
	ds_read_b128 v[216:219], v183 offset:38912
	ds_read_b128 v[220:223], v183 offset:39936
	global_load_lds_dwordx4 v[232:233], off
	v_lshl_add_u64 v[232:233], s[18:19], 0, v[160:161]
	s_mov_b32 m0, s60
	s_nop 0
	global_load_lds_dwordx4 v[232:233], off
	s_waitcnt vmcnt(8)
	s_waitcnt lgkmcnt(0)
	s_barrier
	s_setprio 1
	v_mfma_f32_16x16x32_bf16 v[142:145], v[114:117], v[192:195], v[142:145]
	v_mfma_f32_16x16x32_bf16 v[138:141], v[126:129], v[192:195], v[138:141]
	v_mfma_f32_16x16x32_bf16 v[110:113], v[114:117], v[200:203], v[110:113]
	v_mfma_f32_16x16x32_bf16 v[106:109], v[126:129], v[200:203], v[106:109]
	v_mfma_f32_16x16x32_bf16 v[94:97], v[114:117], v[208:211], v[94:97]
	v_mfma_f32_16x16x32_bf16 v[90:93], v[126:129], v[208:211], v[90:93]
	v_mfma_f32_16x16x32_bf16 v[78:81], v[114:117], v[216:219], v[78:81]
	v_mfma_f32_16x16x32_bf16 v[74:77], v[126:129], v[216:219], v[74:77]
	v_mfma_f32_16x16x32_bf16 v[142:145], v[118:121], v[196:199], v[142:145]
	v_mfma_f32_16x16x32_bf16 v[138:141], v[130:133], v[196:199], v[138:141]
	v_mfma_f32_16x16x32_bf16 v[110:113], v[118:121], v[204:207], v[110:113]
	v_mfma_f32_16x16x32_bf16 v[106:109], v[130:133], v[204:207], v[106:109]
	v_mfma_f32_16x16x32_bf16 v[94:97], v[118:121], v[212:215], v[94:97]
	v_mfma_f32_16x16x32_bf16 v[90:93], v[130:133], v[212:215], v[90:93]
	v_mfma_f32_16x16x32_bf16 v[78:81], v[118:121], v[220:223], v[78:81]
	v_mfma_f32_16x16x32_bf16 v[74:77], v[130:133], v[220:223], v[74:77]
	v_mfma_f32_16x16x32_bf16 v[134:137], v[168:171], v[192:195], v[134:137]
	v_mfma_f32_16x16x32_bf16 v[122:125], v[184:187], v[192:195], v[122:125]
	v_mfma_f32_16x16x32_bf16 v[102:105], v[168:171], v[200:203], v[102:105]
	v_mfma_f32_16x16x32_bf16 v[98:101], v[184:187], v[200:203], v[98:101]
	v_mfma_f32_16x16x32_bf16 v[86:89], v[168:171], v[208:211], v[86:89]
	v_mfma_f32_16x16x32_bf16 v[82:85], v[184:187], v[208:211], v[82:85]
	v_mfma_f32_16x16x32_bf16 v[70:73], v[168:171], v[216:219], v[70:73]
	v_mfma_f32_16x16x32_bf16 v[66:69], v[184:187], v[216:219], v[66:69]
	v_mfma_f32_16x16x32_bf16 v[134:137], v[172:175], v[196:199], v[134:137]
	v_mfma_f32_16x16x32_bf16 v[122:125], v[188:191], v[196:199], v[122:125]
	v_mfma_f32_16x16x32_bf16 v[102:105], v[172:175], v[204:207], v[102:105]
	v_mfma_f32_16x16x32_bf16 v[98:101], v[188:191], v[204:207], v[98:101]
	v_mfma_f32_16x16x32_bf16 v[86:89], v[172:175], v[212:215], v[86:89]
	v_mfma_f32_16x16x32_bf16 v[82:85], v[188:191], v[212:215], v[82:85]
	v_mfma_f32_16x16x32_bf16 v[70:73], v[172:175], v[220:223], v[70:73]
	v_mfma_f32_16x16x32_bf16 v[66:69], v[188:191], v[220:223], v[66:69]
	s_setprio 0
	s_barrier
; #define PG8_STAGE(bufoff, gbase, voff) do { _Pragma("unroll") for (int _i = 0; _i < 2; ++_i) \
;         __builtin_amdgcn_global_load_lds((const unsigned*)((const char*)(gbase) + (voff)[_i]), (PG8_LAS unsigned*)(lds + (bufoff) + ldsw + _i * 8192), 16, 0, 0); } while (0)
; #define PG8_LDA(dst, b, h) do { _Pragma("unroll") for (int m = 0; m < 4; ++m) _Pragma("unroll") for (int k = 0; k < 2; ++k) dst[m][k] = *(const PG8_LAS bf16x8*)(lds + PG8_SA(b, h) + aoff + m * 2048 + k * 1024); } while (0)
; #define PG8_MMA(ai, bj, At, Bt) do { __builtin_amdgcn_s_setprio(1); _Pragma("unroll") for (int m = 0; m < 4; ++m) _Pragma("unroll") for (int n = 0; n < 2; ++n) _Pragma("unroll") for (int k = 0; k < 2; ++k) \
;         acc[ai][bj][m][n] = __builtin_amdgcn_mfma_f32_16x16x32_bf16(Bt[n][k], At[m][k], acc[ai][bj][m][n], 0, 0, 0); __builtin_amdgcn_s_setprio(0); } while (0)
; #define PG8_WAIT_V(n) asm volatile("s_waitcnt vmcnt(" #n ")" ::: "memory")
; #define PG8_WAIT_L(n) asm volatile("s_waitcnt lgkmcnt(" #n ")" ::: "memory")
; #define PG8_BAR __builtin_amdgcn_s_barrier()
; #define PG8_SCHED __builtin_amdgcn_sched_barrier(0)
; template <class Epi, class Sched, bool ALIGN_EPI = false, bool SP2 = false>
; __device__ __forceinline__ void gemm_phase(PG8_LAS unsigned char* lds, const Gemm g, const Sched& S, const Epi& E, int tid_in) {
;     ...
;         for (int t = 0; t < nt; t += 2) {
;             const bool last = (t == nt - 2);
;             const char* a1 = cA + (size_t)(t + 1) * kstep;
;             const char* a2 = last ? nA : cA + (size_t)(t + 2) * kstep; const char* b2 = last ? nB : cB + (size_t)(t + 2) * kstep;
;     ...
;             PG8_LDA(At, 1, 1); PG8_STAGE(PG8_SB(1, 0), b3, voffB); PG8_STAGE(PG8_SB(1, 1), b3 + hstep, voffB); PG8_STAGE(PG8_SA(1, 0), a3, voffA);
;             PG8_WAIT_V(8); PG8_WAIT_L(0); PG8_BAR; PG8_MMA(1, 0, At, B0); PG8_MMA(1, 1, At, B1); PG8_BAR; PG8_SCHED;
	s_add_i32 s17, s17, s54
	v_lshl_add_u64 v[224:225], v[224:225], 0, s[94:95]
	s_mov_b32 m0, s17
	ds_read_b128 v[192:195], v183 offset:49152
	ds_read_b128 v[196:199], v183 offset:50176
	ds_read_b128 v[200:203], v183 offset:51200
	ds_read_b128 v[204:207], v183 offset:52224
	ds_read_b128 v[208:211], v183 offset:53248
	ds_read_b128 v[212:215], v183 offset:54272
	ds_read_b128 v[216:219], v183 offset:55296
	ds_read_b128 v[220:223], v183 offset:56320
	global_load_lds_dwordx4 v[224:225], off
	s_add_i32 m0, s17, 0x2000
	s_add_u32 s0, s0, 0xb0080
	v_lshl_add_u64 v[224:225], v[226:227], 0, s[94:95]
	s_addc_u32 s1, s1, 0
	s_add_i32 s17, s40, s54
	global_load_lds_dwordx4 v[224:225], off
	v_lshl_add_u64 v[224:225], s[0:1], 0, v[162:163]
	s_mov_b32 m0, s17
	s_nop 0
	global_load_lds_dwordx4 v[224:225], off
	v_lshl_add_u64 v[224:225], s[0:1], 0, v[160:161]
	s_add_i32 m0, s17, 0x2000
	s_nop 0
	global_load_lds_dwordx4 v[224:225], off
	v_lshl_add_u64 v[224:225], v[228:229], 0, s[94:95]
	s_mov_b32 m0, s61
	s_nop 0
	global_load_lds_dwordx4 v[224:225], off
	v_lshl_add_u64 v[224:225], v[230:231], 0, s[94:95]
	s_mov_b32 m0, s62
	s_nop 0
	global_load_lds_dwordx4 v[224:225], off
	s_waitcnt vmcnt(8)
	s_waitcnt lgkmcnt(0)
	s_barrier
	s_setprio 1
	v_mfma_f32_16x16x32_bf16 v[62:65], v[114:117], v[192:195], v[62:65]
	v_mfma_f32_16x16x32_bf16 v[58:61], v[126:129], v[192:195], v[58:61]
	v_mfma_f32_16x16x32_bf16 v[46:49], v[114:117], v[200:203], v[46:49]
	v_mfma_f32_16x16x32_bf16 v[42:45], v[126:129], v[200:203], v[42:45]
	v_mfma_f32_16x16x32_bf16 v[30:33], v[114:117], v[208:211], v[30:33]
	v_mfma_f32_16x16x32_bf16 v[26:29], v[126:129], v[208:211], v[26:29]
	v_mfma_f32_16x16x32_bf16 v[14:17], v[114:117], v[216:219], v[14:17]
	v_mfma_f32_16x16x32_bf16 v[10:13], v[126:129], v[216:219], v[10:13]
	v_mfma_f32_16x16x32_bf16 v[62:65], v[118:121], v[196:199], v[62:65]
	v_mfma_f32_16x16x32_bf16 v[58:61], v[130:133], v[196:199], v[58:61]
	v_mfma_f32_16x16x32_bf16 v[46:49], v[118:121], v[204:207], v[46:49]
	v_mfma_f32_16x16x32_bf16 v[42:45], v[130:133], v[204:207], v[42:45]
	v_mfma_f32_16x16x32_bf16 v[30:33], v[118:121], v[212:215], v[30:33]
	v_mfma_f32_16x16x32_bf16 v[26:29], v[130:133], v[212:215], v[26:29]
	v_mfma_f32_16x16x32_bf16 v[14:17], v[118:121], v[220:223], v[14:17]
	v_mfma_f32_16x16x32_bf16 v[10:13], v[130:133], v[220:223], v[10:13]
	v_mfma_f32_16x16x32_bf16 v[54:57], v[168:171], v[192:195], v[54:57]
	v_mfma_f32_16x16x32_bf16 v[50:53], v[184:187], v[192:195], v[50:53]
	v_mfma_f32_16x16x32_bf16 v[38:41], v[168:171], v[200:203], v[38:41]
	v_mfma_f32_16x16x32_bf16 v[34:37], v[184:187], v[200:203], v[34:37]
	v_mfma_f32_16x16x32_bf16 v[22:25], v[168:171], v[208:211], v[22:25]
	v_mfma_f32_16x16x32_bf16 v[18:21], v[184:187], v[208:211], v[18:21]
	v_mfma_f32_16x16x32_bf16 v[6:9], v[168:171], v[216:219], v[6:9]
	v_mfma_f32_16x16x32_bf16 v[2:5], v[184:187], v[216:219], v[2:5]
	v_mfma_f32_16x16x32_bf16 v[54:57], v[172:175], v[196:199], v[54:57]
	v_mfma_f32_16x16x32_bf16 v[50:53], v[188:191], v[196:199], v[50:53]
	v_mfma_f32_16x16x32_bf16 v[38:41], v[172:175], v[204:207], v[38:41]
	v_mfma_f32_16x16x32_bf16 v[34:37], v[188:191], v[204:207], v[34:37]
	v_mfma_f32_16x16x32_bf16 v[22:25], v[172:175], v[212:215], v[22:25]
	v_mfma_f32_16x16x32_bf16 v[18:21], v[188:191], v[212:215], v[18:21]
	v_mfma_f32_16x16x32_bf16 v[6:9], v[172:175], v[220:223], v[6:9]
	v_mfma_f32_16x16x32_bf16 v[2:5], v[188:191], v[220:223], v[2:5]
	s_setprio 0
	s_barrier
	s_add_i32 s69, s69, 2
	s_add_u32 s67, s67, 0x100
	s_addc_u32 s68, s68, 0
	s_cmp_gt_u32 s69, 41
	s_mov_b64 s[40:41], s[44:45]
	s_cbranch_scc0 .LBB0_1115
	s_and_b64 vcc, exec, s[8:9]
	s_cbranch_vccz .LBB0_1118
	s_barrier
